# S5 prompt: loop unrolled x4 with double-buffered u prefetch, packed bf16 transpose, hoisted prologue loads; P7 11 rows in flight
# speedup vs baseline: 1.0394x; 1.0225x over previous
.LBB0_321:
	s_and_b32 s48, s47, 63
	s_lshl_b32 s0, s48, 2
	v_readlane_b32 s80, v242, 37
	v_mov_b32_e32 v3, v0
	v_mov_b32_e32 v4, s0
	v_readlane_b32 s84, v242, 41
	v_readlane_b32 s85, v242, 42
	s_lshl_b32 s18, s48, 6
	s_waitcnt vmcnt(0)
	v_and_b32_e32 v58, 63, v3
	v_readlane_b32 s82, v242, 39
	v_readlane_b32 s83, v242, 40
	global_load_dword v6, v4, s[84:85]
	v_or_b32_e32 v4, s18, v58
	v_lshlrev_b32_e32 v5, 2, v4
	v_readlane_b32 s81, v242, 38
	s_nop 0
	global_load_dword v4, v5, s[82:83]
	s_nop 2
	global_load_dword v5, v5, s[80:81]
	s_brev_b32 s0, 18
	v_readlane_b32 s86, v242, 43
	v_readlane_b32 s87, v242, 44
	v_readlane_b32 s88, v242, 45
	v_readlane_b32 s89, v242, 46
	v_readlane_b32 s90, v242, 47
	v_readlane_b32 s91, v242, 48
	v_readlane_b32 s92, v242, 49
	v_readlane_b32 s93, v242, 50
	v_readlane_b32 s94, v242, 51
	v_readlane_b32 s95, v242, 52
	v_and_b32_e32 v140, 15, v58
	v_lshrrev_b32_e32 v141, 4, v58
	s_lshl_b32 s26, s48, 12
	v_lshlrev_b32_e32 v131, 6, v140
	v_lshl_add_u32 v131, v141, 5, v131
	v_add_u32_e32 v131, s26, v131
	v_lshlrev_b32_e32 v240, 8, v140
	v_lshl_add_u32 v240, v141, 4, v240
	v_add_u32_e32 v240, s26, v240
	s_ashr_i32 s27, s47, 6
	s_lshl_b32 s27, s27, 11
	v_lshrrev_b32_e32 v218, 6, v3
	v_lshl_add_u32 v218, v218, 8, v140
	v_add_u32_e32 v218, s27, v218
	s_movk_i32 s27, 0x2400
	v_mul_u32_u24_e32 v218, s27, v218
	s_lshl_b32 s27, s48, 5
	s_add_u32 s27, s27, 0x1c00
	v_lshl_add_u32 v218, v141, 4, v218
	v_add_u32_e32 v218, s27, v218
	v_mov_b32_e32 v219, 0
	v_lshl_add_u64 v[84:85], v[218:219], 0, s[60:61]
	s_mov_b32 exec_lo, -1
	s_mov_b32 exec_hi, 0
	global_load_dwordx4 v[186:189], v131, s[86:87] offset:0
	global_load_dwordx4 v[190:193], v131, s[86:87] offset:16
	global_load_dwordx4 v[194:197], v131, s[88:89] offset:0
	global_load_dwordx4 v[198:201], v131, s[88:89] offset:16
	global_load_dwordx4 v[202:205], v131, s[86:87] offset:1024
	global_load_dwordx4 v[206:209], v131, s[86:87] offset:1040
	global_load_dwordx4 v[210:213], v131, s[88:89] offset:1024
	global_load_dwordx4 v[214:217], v131, s[88:89] offset:1040
	global_load_dwordx4 v[220:223], v131, s[86:87] offset:2048
	global_load_dwordx4 v[224:227], v131, s[86:87] offset:2064
	global_load_dwordx4 v[228:231], v131, s[88:89] offset:2048
	global_load_dwordx4 v[232:235], v131, s[88:89] offset:2064
	global_load_dwordx4 v[236:239], v131, s[86:87] offset:3072
	global_load_dwordx4 v[154:157], v131, s[86:87] offset:3088
	global_load_dwordx4 v[158:161], v131, s[88:89] offset:3072
	global_load_dwordx4 v[170:173], v131, s[88:89] offset:3088
	s_mov_b64 exec, -1
	global_load_dwordx4 v[142:145], v240, s[90:91] offset:0
	global_load_dwordx4 v[146:149], v240, s[90:91] offset:64
	global_load_dwordx4 v[150:153], v240, s[90:91] offset:128
	global_load_dwordx4 v[162:165], v240, s[90:91] offset:192
	global_load_dwordx4 v[166:169], v240, s[92:93] offset:0
	global_load_dwordx4 v[174:177], v240, s[92:93] offset:64
	global_load_dwordx4 v[178:181], v240, s[92:93] offset:128
	global_load_dwordx4 v[104:107], v240, s[92:93] offset:192
	s_waitcnt vmcnt(26)
	v_mul_f32_e32 v7, 0x3fb8aa3b, v6
	v_fma_f32 v8, v6, s28, -v7
	v_rndne_f32_e32 v9, v7
	v_fmac_f32_e32 v8, 0x32a5705f, v6
	v_sub_f32_e32 v7, v7, v9
	v_add_f32_e32 v7, v7, v8
	v_cvt_i32_f32_e32 v9, v9
	v_exp_f32_e32 v7, v7
	v_cmp_ngt_f32_e32 vcc, s29, v6
	v_ldexp_f32 v7, v7, v9
	s_nop 0
	v_cndmask_b32_e32 v7, 0, v7, vcc
	v_cmp_nlt_f32_e32 vcc, s30, v6
	s_nop 1
	v_cndmask_b32_e32 v8, v118, v7, vcc
	s_waitcnt vmcnt(25)
	v_mul_f32_e32 v6, v4, v8
	v_and_b32_e32 v7, 0x7fffffff, v6
	v_lshrrev_b32_e32 v9, 23, v7
	v_and_b32_e32 v10, 0x7fffff, v7
	v_cmp_nlt_f32_e64 s[8:9], |v6|, s0
	v_add_u32_e32 v12, 0xffffff88, v9
	v_or_b32_e32 v11, 0x800000, v10
	s_and_saveexec_b64 s[0:1], s[8:9]
	s_xor_b64 s[16:17], exec, s[0:1]
	s_cbranch_execz .LBB0_323
	v_mad_u64_u32 v[14:15], s[6:7], v11, s31, 0
	v_mov_b32_e32 v16, v15
	v_mov_b32_e32 v17, v2
	v_mad_u64_u32 v[16:17], s[6:7], v11, s33, v[16:17]
	v_mov_b32_e32 v18, v17
	v_mov_b32_e32 v19, v2
	v_mad_u64_u32 v[18:19], s[6:7], v11, s34, v[18:19]
	v_cmp_lt_u32_e32 vcc, 63, v12
	v_mov_b32_e32 v20, v19
	v_mov_b32_e32 v21, v2
	v_cndmask_b32_e32 v9, 0, v121, vcc
	v_mad_u64_u32 v[20:21], s[6:7], v11, s35, v[20:21]
	v_add_u32_e32 v9, v9, v12
	v_mov_b32_e32 v22, v21
	v_mov_b32_e32 v23, v2
	v_cmp_lt_u32_e64 s[0:1], 31, v9
	v_mad_u64_u32 v[22:23], s[6:7], v11, s36, v[22:23]
	s_nop 0
	v_cndmask_b32_e64 v10, 0, v122, s[0:1]
	v_mov_b32_e32 v24, v23
	v_mov_b32_e32 v25, v2
	v_add_u32_e32 v9, v10, v9
	v_mad_u64_u32 v[24:25], s[6:7], v11, s37, v[24:25]
	v_cmp_lt_u32_e64 s[4:5], 31, v9
	v_mov_b32_e32 v26, v25
	v_mov_b32_e32 v27, v2
	v_cndmask_b32_e64 v10, 0, v122, s[4:5]
	v_mad_u64_u32 v[26:27], s[6:7], v11, s38, v[26:27]
	v_add_u32_e32 v9, v10, v9
	v_cndmask_b32_e32 v10, v24, v20, vcc
	v_cndmask_b32_e32 v13, v26, v22, vcc
	v_cndmask_b32_e32 v17, v27, v24, vcc
	v_cndmask_b32_e64 v15, v13, v10, s[0:1]
	v_cndmask_b32_e64 v13, v17, v13, s[0:1]
	v_cndmask_b32_e32 v17, v22, v18, vcc
	v_cndmask_b32_e64 v10, v10, v17, s[0:1]
	v_cndmask_b32_e64 v13, v13, v15, s[4:5]
	v_cndmask_b32_e64 v15, v15, v10, s[4:5]
	v_sub_u32_e32 v19, 32, v9
	v_alignbit_b32 v21, v13, v15, v19
	v_cmp_eq_u32_e64 s[6:7], 0, v9
	v_cndmask_b32_e32 v14, v18, v14, vcc
	s_nop 0
	v_cndmask_b32_e64 v9, v21, v13, s[6:7]
	v_cndmask_b32_e32 v13, v20, v16, vcc
	v_cndmask_b32_e64 v16, v17, v13, s[0:1]
	v_cndmask_b32_e64 v10, v10, v16, s[4:5]
	v_alignbit_b32 v17, v15, v10, v19
	v_cndmask_b32_e64 v13, v13, v14, s[0:1]
	v_cndmask_b32_e64 v15, v17, v15, s[6:7]
	v_bfe_u32 v21, v9, 29, 1
	v_cndmask_b32_e64 v13, v16, v13, s[4:5]
	v_alignbit_b32 v17, v9, v15, 30
	v_sub_u32_e32 v22, 0, v21
	v_alignbit_b32 v14, v10, v13, v19
	v_xor_b32_e32 v17, v17, v22
	v_cndmask_b32_e64 v10, v14, v10, s[6:7]
	v_alignbit_b32 v14, v15, v10, 30
	v_ffbh_u32_e32 v15, v17
	v_min_u32_e32 v15, 32, v15
	v_alignbit_b32 v10, v10, v13, 30
	v_xor_b32_e32 v14, v14, v22
	v_sub_u32_e32 v16, 31, v15
	v_xor_b32_e32 v10, v10, v22
	v_alignbit_b32 v17, v17, v14, v16
	v_alignbit_b32 v10, v14, v10, v16
	v_alignbit_b32 v13, v17, v10, 9
	v_ffbh_u32_e32 v14, v13
	v_min_u32_e32 v14, 32, v14
	v_lshrrev_b32_e32 v20, 29, v9
	v_not_b32_e32 v16, v14
	v_alignbit_b32 v10, v13, v10, v16
	v_lshlrev_b32_e32 v13, 31, v20
	v_or_b32_e32 v16, 0x33000000, v13
	v_add_lshl_u32 v14, v14, v15, 23
	v_lshrrev_b32_e32 v10, 9, v10
	v_sub_u32_e32 v14, v16, v14
	v_or_b32_e32 v13, 0.5, v13
	v_lshlrev_b32_e32 v15, 23, v15
	v_or_b32_e32 v10, v14, v10
	v_lshrrev_b32_e32 v14, 9, v17
	v_sub_u32_e32 v13, v13, v15
	v_or_b32_e32 v13, v14, v13
	v_mul_f32_e32 v14, 0x3fc90fda, v13
	v_fma_f32 v15, v13, s39, -v14
	v_fmac_f32_e32 v15, 0x33a22168, v13
	v_fmac_f32_e32 v15, 0x3fc90fda, v10
	v_lshrrev_b32_e32 v9, 30, v9
	v_add_f32_e32 v10, v14, v15
	v_add_u32_e32 v9, v21, v9

.LBB0_329:
	s_or_b64 exec, exec, s[0:1]
	s_waitcnt vmcnt(24)
	v_mul_f32_e32 v8, v5, v8
	v_mul_f32_e32 v11, 0x3fb8aa3b, v8
	v_fma_f32 v12, v8, s28, -v11
	v_rndne_f32_e32 v15, v11
	v_fmac_f32_e32 v12, 0x32a5705f, v8
	v_sub_f32_e32 v11, v11, v15
	v_add_f32_e32 v11, v11, v12
	v_cvt_i32_f32_e32 v12, v15
	v_exp_f32_e32 v11, v11
	v_cmp_ngt_f32_e32 vcc, s29, v8
	s_brev_b32 s0, 1
	v_ashrrev_i32_e32 v76, 6, v3
	v_ldexp_f32 v11, v11, v12
	v_cndmask_b32_e32 v11, 0, v11, vcc
	v_cmp_nlt_f32_e32 vcc, s30, v8
	v_mul_f32_e32 v8, v10, v10
	v_and_b32_e32 v59, 15, v3
	v_cndmask_b32_e32 v42, v118, v11, vcc
	v_fmamk_f32 v11, v8, 0xb94c1982, v119
	v_fmaak_f32 v11, v8, v11, 0xbe2aaa9d
	v_mul_f32_e32 v11, v8, v11
	v_fmac_f32_e32 v10, v10, v11
	v_fmamk_f32 v11, v8, 0x37d75334, v120
	v_fmaak_f32 v11, v8, v11, 0x3d2aabf7
	v_fmaak_f32 v11, v8, v11, 0xbf000004
	v_fma_f32 v8, v8, v11, 1.0
	v_and_b32_e32 v11, 1, v9
	v_cmp_eq_u32_e32 vcc, 0, v11
	v_lshlrev_b32_e32 v9, 30, v9
	v_lshl_add_u32 v11, v76, 9, s41
	v_cndmask_b32_e64 v8, -v10, v8, vcc
	v_bitop3_b32 v8, v9, v8, s0 bitop3:0x6c
	s_movk_i32 s0, 0x1f8
	v_cmp_class_f32_e64 vcc, v6, s0
	v_xor_b32_e32 v6, v7, v6
	v_mul_f32_e32 v7, v4, v4
	v_cndmask_b32_e32 v43, v123, v8, vcc
	v_mul_f32_e32 v8, v14, v14
	v_fmamk_f32 v9, v8, 0xb94c1982, v119
	v_fmaak_f32 v9, v8, v9, 0xbe2aaa9d
	v_mul_f32_e32 v9, v8, v9
	v_fmac_f32_e32 v14, v14, v9
	v_fmamk_f32 v9, v8, 0x37d75334, v120
	v_fmaak_f32 v9, v8, v9, 0x3d2aabf7
	v_fmaak_f32 v9, v8, v9, 0xbf000004
	v_fma_f32 v8, v8, v9, 1.0
	v_and_b32_e32 v9, 1, v13
	v_cmp_eq_u32_e64 s[0:1], 0, v9
	v_lshlrev_b32_e32 v9, 30, v13
	v_and_b32_e32 v9, 0x80000000, v9
	v_cndmask_b32_e64 v8, v8, v14, s[0:1]
	v_xor_b32_e32 v6, v6, v9
	v_xor_b32_e32 v6, v6, v8
	v_cndmask_b32_e32 v6, v123, v6, vcc
	v_mul_f32_e32 v78, v42, v6
	v_fma_f32 v6, v42, v43, -1.0
	v_mul_f32_e32 v8, v4, v78
	v_fmac_f32_e32 v7, v5, v5
	v_fmac_f32_e32 v8, v5, v6
	v_div_scale_f32 v9, s[0:1], v7, v7, v8
	v_rcp_f32_e32 v10, v9
	v_mul_f32_e32 v4, v4, v6
	v_fma_f32 v4, v5, v78, -v4
	v_div_scale_f32 v5, s[0:1], v7, v7, v4
	v_fma_f32 v12, -v9, v10, 1.0
	v_fmac_f32_e32 v10, v12, v10
	v_div_scale_f32 v12, vcc, v8, v7, v8
	v_mul_f32_e32 v13, v12, v10
	v_rcp_f32_e32 v6, v5
	v_fma_f32 v14, -v9, v13, v12
	v_fmac_f32_e32 v13, v14, v10
	v_fma_f32 v9, -v9, v13, v12
	v_div_fmas_f32 v9, v9, v10, v13
	v_fma_f32 v10, -v5, v6, 1.0
	v_fmac_f32_e32 v6, v10, v6
	v_div_scale_f32 v10, vcc, v4, v7, v4
	v_mul_f32_e32 v12, v10, v6
	v_fma_f32 v13, -v5, v12, v10
	v_fmac_f32_e32 v12, v13, v6
	v_fma_f32 v5, -v5, v12, v10
	v_div_fmas_f32 v5, v5, v6, v12
	v_div_fixup_f32 v8, v9, v7, v8
	v_lshl_add_u32 v9, v58, 2, v11
	v_div_fixup_f32 v4, v5, v7, v4
	ds_write2st64_b32 v9, v8, v4 offset1:1
	v_lshrrev_b32_e32 v60, 4, v58
	s_waitcnt lgkmcnt(0)
	v_lshl_add_u32 v44, v59, 2, v11
	v_mov_b32_e32 v6, 0
	v_mov_b32_e32 v7, 0
	v_mov_b32_e32 v8, 0
	v_mov_b32_e32 v9, 0
	v_mov_b32_e32 v10, 0
	v_mov_b32_e32 v11, 0
	v_mov_b32_e32 v12, 0
	v_mov_b32_e32 v13, 0
	v_mov_b32_e32 v14, 0
	v_mov_b32_e32 v15, 0
	v_mov_b32_e32 v16, 0
	v_mov_b32_e32 v17, 0
	v_mov_b32_e32 v18, 0
	v_mov_b32_e32 v19, 0
	v_mov_b32_e32 v20, 0
	v_mov_b32_e32 v21, 0
	v_mov_b32_e32 v22, 0
	v_mov_b32_e32 v23, 0
	v_mov_b32_e32 v24, 0
	v_mov_b32_e32 v25, 0
	v_mov_b32_e32 v26, 0
	v_mov_b32_e32 v27, 0
	v_mov_b32_e32 v28, 0
	v_mov_b32_e32 v29, 0
	v_mov_b32_e32 v30, 0
	v_mov_b32_e32 v31, 0
	v_mov_b32_e32 v32, 0
	v_mov_b32_e32 v33, 0
	v_mov_b32_e32 v34, 0
	v_mov_b32_e32 v35, 0
	v_mov_b32_e32 v36, 0
	v_mov_b32_e32 v37, 0
	s_waitcnt vmcnt(8)
	s_mov_b32 exec_lo, -1
	s_mov_b32 exec_hi, 0
	ds_read2_b32 v[4:5], v44 offset0:0 offset1:64
	s_waitcnt lgkmcnt(0)
	v_mul_f32_e32 v62, v194, v5
	v_mul_f32_e32 v63, v195, v5
	v_mul_f32_e32 v64, v196, v5
	v_mul_f32_e32 v65, v197, v5
	v_mul_f32_e32 v66, v198, v5
	v_mul_f32_e32 v67, v199, v5
	v_mul_f32_e32 v68, v200, v5
	v_mul_f32_e32 v69, v201, v5
	v_fma_f32 v62, v186, v4, -v62
	v_fma_f32 v63, v187, v4, -v63
	v_fma_f32 v64, v188, v4, -v64
	v_fma_f32 v65, v189, v4, -v65
	v_fma_f32 v66, v190, v4, -v66
	v_fma_f32 v67, v191, v4, -v67
	v_fma_f32 v68, v192, v4, -v68
	v_fma_f32 v69, v193, v4, -v69
	v_cvt_pk_bf16_f32 v10, v62, v63
	v_cvt_pk_bf16_f32 v11, v64, v65
	v_cvt_pk_bf16_f32 v12, v66, v67
	v_cvt_pk_bf16_f32 v13, v68, v69
	v_mul_f32_e32 v194, v194, v4
	v_mul_f32_e32 v195, v195, v4
	v_mul_f32_e32 v196, v196, v4
	v_mul_f32_e32 v197, v197, v4
	v_mul_f32_e32 v198, v198, v4
	v_mul_f32_e32 v199, v199, v4
	v_mul_f32_e32 v200, v200, v4
	v_mul_f32_e32 v201, v201, v4
	v_fmac_f32_e32 v194, v186, v5
	v_fmac_f32_e32 v195, v187, v5
	v_fmac_f32_e32 v196, v188, v5
	v_fmac_f32_e32 v197, v189, v5
	v_fmac_f32_e32 v198, v190, v5
	v_fmac_f32_e32 v199, v191, v5
	v_fmac_f32_e32 v200, v192, v5
	v_fmac_f32_e32 v201, v193, v5
	v_cvt_pk_bf16_f32 v26, v194, v195
	v_cvt_pk_bf16_f32 v27, v196, v197
	v_cvt_pk_bf16_f32 v28, v198, v199
	v_cvt_pk_bf16_f32 v29, v200, v201
	ds_read2_b32 v[4:5], v44 offset0:16 offset1:80
	s_waitcnt lgkmcnt(0)
	v_mul_f32_e32 v62, v210, v5
	v_mul_f32_e32 v63, v211, v5
	v_mul_f32_e32 v64, v212, v5
	v_mul_f32_e32 v65, v213, v5
	v_mul_f32_e32 v66, v214, v5
	v_mul_f32_e32 v67, v215, v5
	v_mul_f32_e32 v68, v216, v5
	v_mul_f32_e32 v69, v217, v5
	v_fma_f32 v62, v202, v4, -v62
	v_fma_f32 v63, v203, v4, -v63
	v_fma_f32 v64, v204, v4, -v64
	v_fma_f32 v65, v205, v4, -v65
	v_fma_f32 v66, v206, v4, -v66
	v_fma_f32 v67, v207, v4, -v67
	v_fma_f32 v68, v208, v4, -v68
	v_fma_f32 v69, v209, v4, -v69
	v_cvt_pk_bf16_f32 v6, v62, v63
	v_cvt_pk_bf16_f32 v7, v64, v65
	v_cvt_pk_bf16_f32 v8, v66, v67
	v_cvt_pk_bf16_f32 v9, v68, v69
	v_mul_f32_e32 v210, v210, v4
	v_mul_f32_e32 v211, v211, v4
	v_mul_f32_e32 v212, v212, v4
	v_mul_f32_e32 v213, v213, v4
	v_mul_f32_e32 v214, v214, v4
	v_mul_f32_e32 v215, v215, v4
	v_mul_f32_e32 v216, v216, v4
	v_mul_f32_e32 v217, v217, v4
	v_fmac_f32_e32 v210, v202, v5
	v_fmac_f32_e32 v211, v203, v5
	v_fmac_f32_e32 v212, v204, v5
	v_fmac_f32_e32 v213, v205, v5
	v_fmac_f32_e32 v214, v206, v5
	v_fmac_f32_e32 v215, v207, v5
	v_fmac_f32_e32 v216, v208, v5
	v_fmac_f32_e32 v217, v209, v5
	v_cvt_pk_bf16_f32 v22, v210, v211
	v_cvt_pk_bf16_f32 v23, v212, v213
	v_cvt_pk_bf16_f32 v24, v214, v215
	v_cvt_pk_bf16_f32 v25, v216, v217
	ds_read2_b32 v[4:5], v44 offset0:32 offset1:96
	s_waitcnt lgkmcnt(0)
	v_mul_f32_e32 v62, v228, v5
	v_mul_f32_e32 v63, v229, v5
	v_mul_f32_e32 v64, v230, v5
	v_mul_f32_e32 v65, v231, v5
	v_mul_f32_e32 v66, v232, v5
	v_mul_f32_e32 v67, v233, v5
	v_mul_f32_e32 v68, v234, v5
	v_mul_f32_e32 v69, v235, v5
	v_fma_f32 v62, v220, v4, -v62
	v_fma_f32 v63, v221, v4, -v63
	v_fma_f32 v64, v222, v4, -v64
	v_fma_f32 v65, v223, v4, -v65
	v_fma_f32 v66, v224, v4, -v66
	v_fma_f32 v67, v225, v4, -v67
	v_fma_f32 v68, v226, v4, -v68
	v_fma_f32 v69, v227, v4, -v69
	v_cvt_pk_bf16_f32 v18, v62, v63
	v_cvt_pk_bf16_f32 v19, v64, v65
	v_cvt_pk_bf16_f32 v20, v66, v67
	v_cvt_pk_bf16_f32 v21, v68, v69
	v_mul_f32_e32 v228, v228, v4
	v_mul_f32_e32 v229, v229, v4
	v_mul_f32_e32 v230, v230, v4
	v_mul_f32_e32 v231, v231, v4
	v_mul_f32_e32 v232, v232, v4
	v_mul_f32_e32 v233, v233, v4
	v_mul_f32_e32 v234, v234, v4
	v_mul_f32_e32 v235, v235, v4
	v_fmac_f32_e32 v228, v220, v5
	v_fmac_f32_e32 v229, v221, v5
	v_fmac_f32_e32 v230, v222, v5
	v_fmac_f32_e32 v231, v223, v5
	v_fmac_f32_e32 v232, v224, v5
	v_fmac_f32_e32 v233, v225, v5
	v_fmac_f32_e32 v234, v226, v5
	v_fmac_f32_e32 v235, v227, v5
	v_cvt_pk_bf16_f32 v34, v228, v229
	v_cvt_pk_bf16_f32 v35, v230, v231
	v_cvt_pk_bf16_f32 v36, v232, v233
	v_cvt_pk_bf16_f32 v37, v234, v235
	ds_read2_b32 v[4:5], v44 offset0:48 offset1:112
	s_waitcnt lgkmcnt(0)
	v_mul_f32_e32 v62, v158, v5
	v_mul_f32_e32 v63, v159, v5
	v_mul_f32_e32 v64, v160, v5
	v_mul_f32_e32 v65, v161, v5
	v_mul_f32_e32 v66, v170, v5
	v_mul_f32_e32 v67, v171, v5
	v_mul_f32_e32 v68, v172, v5
	v_mul_f32_e32 v69, v173, v5
	v_fma_f32 v62, v236, v4, -v62
	v_fma_f32 v63, v237, v4, -v63
	v_fma_f32 v64, v238, v4, -v64
	v_fma_f32 v65, v239, v4, -v65
	v_fma_f32 v66, v154, v4, -v66
	v_fma_f32 v67, v155, v4, -v67
	v_fma_f32 v68, v156, v4, -v68
	v_fma_f32 v69, v157, v4, -v69
	v_cvt_pk_bf16_f32 v14, v62, v63
	v_cvt_pk_bf16_f32 v15, v64, v65
	v_cvt_pk_bf16_f32 v16, v66, v67
	v_cvt_pk_bf16_f32 v17, v68, v69
	v_mul_f32_e32 v158, v158, v4
	v_mul_f32_e32 v159, v159, v4
	v_mul_f32_e32 v160, v160, v4
	v_mul_f32_e32 v161, v161, v4
	v_mul_f32_e32 v170, v170, v4
	v_mul_f32_e32 v171, v171, v4
	v_mul_f32_e32 v172, v172, v4
	v_mul_f32_e32 v173, v173, v4
	v_fmac_f32_e32 v158, v236, v5
	v_fmac_f32_e32 v159, v237, v5
	v_fmac_f32_e32 v160, v238, v5
	v_fmac_f32_e32 v161, v239, v5
	v_fmac_f32_e32 v170, v154, v5
	v_fmac_f32_e32 v171, v155, v5
	v_fmac_f32_e32 v172, v156, v5
	v_fmac_f32_e32 v173, v157, v5
	v_cvt_pk_bf16_f32 v30, v158, v159
	v_cvt_pk_bf16_f32 v31, v160, v161
	v_cvt_pk_bf16_f32 v32, v170, v171
	v_cvt_pk_bf16_f32 v33, v172, v173
	s_mov_b64 exec, -1
	v_mov_b32_e32 v186, 0
	v_mov_b32_e32 v187, 0
	v_mov_b32_e32 v188, 0
	v_mov_b32_e32 v189, 0
	v_mov_b32_e32 v190, 0
	v_mov_b32_e32 v191, 0
	v_mov_b32_e32 v192, 0
	v_mov_b32_e32 v193, 0
	v_mov_b32_e32 v194, 0
	v_mov_b32_e32 v195, 0
	v_mov_b32_e32 v196, 0
	v_mov_b32_e32 v197, 0
	v_mov_b32_e32 v198, 0
	v_mov_b32_e32 v199, 0
	v_mov_b32_e32 v200, 0
	v_mov_b32_e32 v201, 0
	v_mov_b32_e32 v202, 0
	v_mov_b32_e32 v203, 0
	v_mov_b32_e32 v204, 0
	v_mov_b32_e32 v205, 0
	v_mov_b32_e32 v206, 0
	v_mov_b32_e32 v207, 0
	v_mov_b32_e32 v208, 0
	v_mov_b32_e32 v209, 0
	v_mov_b32_e32 v210, 0
	v_mov_b32_e32 v211, 0
	v_mov_b32_e32 v212, 0
	v_mov_b32_e32 v213, 0
	v_mov_b32_e32 v214, 0
	v_mov_b32_e32 v215, 0
	v_mov_b32_e32 v216, 0
	v_mov_b32_e32 v217, 0
	s_mov_b32 exec_lo, -1
	s_mov_b32 exec_hi, 0
	global_load_dwordx4 v[186:189], v[84:85], off
	s_mov_b64 s[26:27], 0x24000
	v_lshl_add_u64 v[4:5], v[84:85], 0, s[26:27]
	global_load_dwordx4 v[190:193], v[4:5], off
	s_add_u32 s26, s26, 0x24000
	s_addc_u32 s27, s27, 0
	v_lshl_add_u64 v[4:5], v[84:85], 0, s[26:27]
	global_load_dwordx4 v[194:197], v[4:5], off
	s_add_u32 s26, s26, 0x24000
	s_addc_u32 s27, s27, 0
	v_lshl_add_u64 v[4:5], v[84:85], 0, s[26:27]
	global_load_dwordx4 v[198:201], v[4:5], off
	s_mov_b64 exec, -1
	s_lshl_b32 s0, s48, 12
	v_readlane_b32 s80, v242, 37
	v_lshlrev_b32_e32 v61, 3, v60
	v_lshl_or_b32 v4, v59, 8, s0
	v_mov_b32_e32 v5, v2
	v_readlane_b32 s90, v242, 47
	v_readlane_b32 s91, v242, 48
	v_readlane_b32 s92, v242, 49
	v_readlane_b32 s93, v242, 50
	v_lshl_add_u64 v[38:39], s[90:91], 0, v[4:5]
	v_lshlrev_b32_e32 v40, 1, v61
	v_mov_b32_e32 v41, v2
	v_lshl_add_u64 v[38:39], v[38:39], 0, v[40:41]
	v_lshl_add_u64 v[4:5], s[92:93], 0, v[4:5]
	v_lshl_add_u64 v[4:5], v[4:5], 0, v[40:41]
	s_ashr_i32 s16, s47, 6
	s_and_b32 s6, s46, 63
	s_movk_i32 s12, 0x2800
	s_ashr_i32 s17, s16, 31
	v_readlane_b32 s94, v242, 51
	v_mul_lo_u32 v56, v76, s12
	s_lshl_b32 s12, s6, 5
	s_lshl_b64 s[20:21], s[16:17], 11
	v_readlane_b32 s95, v242, 52
	v_lshlrev_b32_e32 v40, 7, v76
	v_ashrrev_i32_e32 v77, 31, v76
	s_add_u32 s18, s94, s18
	v_lshlrev_b32_e32 v41, 4, v60
	v_lshlrev_b32_e32 v82, 2, v58
	v_lshlrev_b64 v[38:39], 8, v[76:77]
	v_lshlrev_b32_e32 v40, 2, v40
	v_add_u32_e32 v74, 0, v56
	s_addc_u32 s19, s95, 0
	v_add3_u32 v77, s42, v40, v82
	v_add_u32_e32 v75, v74, v41
	v_lshl_add_u64 v[56:57], v[38:39], 0, s[20:21]
	global_load_dwordx4 v[38:41], v41, s[18:19]
	v_mov_b64_e32 v[4:5], s[60:61]
	v_or_b32_e32 v56, v56, v59
	v_mad_u64_u32 v[4:5], s[18:19], v56, s43, v[4:5]
	s_mov_b32 s7, s13
	s_lshl_b32 s6, s48, 5
	v_mad_i32_i24 v5, v57, s43, v5
	v_mul_f32_e32 v80, v42, v43
	v_mov_b32_e32 v43, v2
	v_lshlrev_b32_e32 v42, 1, v61
	v_lshl_add_u64 v[4:5], v[4:5], 0, s[6:7]
	v_lshl_add_u64 v[4:5], v[4:5], 0, v[42:43]
	v_lshl_add_u64 v[84:85], v[4:5], 0, s[14:15]
	v_cmp_lt_u32_e32 vcc, 31, v58
	v_cmp_gt_u32_e64 s[4:5], 32, v58
	v_mul_u32_u24_e32 v60, 0x280, v60
	v_cmp_eq_u32_e64 s[0:1], 7, v76
	v_cmp_lt_i32_e64 s[8:9], 0, v76
	v_mov_b32_e32 v81, v80
	v_mov_b32_e32 v79, v78
	v_add_u32_e32 v83, s44, v82
	s_mov_b64 s[20:21], -1
	s_mov_b64 s[22:23], 0
	s_xor_b64 s[18:19], vcc, -1
	v_readlane_b32 s81, v242, 38
	v_readlane_b32 s82, v242, 39
	v_readlane_b32 s83, v242, 40
	v_readlane_b32 s84, v242, 41
	v_readlane_b32 s85, v242, 42
	v_readlane_b32 s86, v242, 43
	v_readlane_b32 s87, v242, 44
	v_readlane_b32 s88, v242, 45
	v_readlane_b32 s89, v242, 46
	s_waitcnt vmcnt(5)
	v_cvt_pk_bf16_f32 v42, v142, -v166
	v_cvt_pk_bf16_f32 v43, v143, -v167
	v_cvt_pk_bf16_f32 v44, v144, -v168
	v_cvt_pk_bf16_f32 v45, v145, -v169
	v_cvt_pk_bf16_f32 v46, v146, -v174
	v_cvt_pk_bf16_f32 v47, v147, -v175
	v_cvt_pk_bf16_f32 v48, v148, -v176
	v_cvt_pk_bf16_f32 v49, v149, -v177
	v_cvt_pk_bf16_f32 v50, v150, -v178
	v_cvt_pk_bf16_f32 v51, v151, -v179
	v_cvt_pk_bf16_f32 v52, v152, -v180
	v_cvt_pk_bf16_f32 v53, v153, -v181
	v_cvt_pk_bf16_f32 v54, v162, -v104
	v_cvt_pk_bf16_f32 v55, v163, -v105
	v_cvt_pk_bf16_f32 v56, v164, -v106
	v_cvt_pk_bf16_f32 v57, v165, -v107
	v_add_f32_e32 v5, v80, v80
	v_mul_f32_e32 v4, v78, v78
	v_mul_f32_e32 v5, v5, v78
	v_mul_u32_u24_e32 v62, 0x50, v58
	v_fma_f32 v4, v80, v80, -v4
	v_mul_f32_e32 v58, v5, v5
	v_fma_f32 v58, v4, v4, -v58
	v_add_f32_e32 v4, v4, v4
	v_mul_f32_e32 v4, v5, v4
	v_mul_f32_e32 v5, v4, v4
	v_fma_f32 v5, v58, v58, -v5
	v_add_f32_e32 v58, v58, v58
	v_mul_f32_e32 v4, v4, v58
	v_mul_f32_e32 v58, v4, v4
	v_fma_f32 v58, v5, v5, -v58
	v_add_f32_e32 v5, v5, v5
	v_mul_f32_e32 v4, v4, v5
	v_mul_f32_e32 v5, v4, v4
	v_fma_f32 v5, v58, v58, -v5
	v_add_f32_e32 v58, v58, v58
	v_mul_f32_e32 v4, v4, v58
	v_mul_f32_e32 v58, v4, v4
	v_fma_f32 v58, v5, v5, -v58
	v_add_f32_e32 v5, v5, v5
	v_mul_f32_e32 v4, v4, v5
	v_mul_f32_e32 v5, v4, v4
	v_fma_f32 v5, v58, v58, -v5
	v_add_f32_e32 v58, v58, v58
	v_mul_f32_e32 v4, v4, v58
	v_mul_f32_e32 v58, v4, v4
	v_fma_f32 v86, v5, v5, -v58
	v_add_f32_e32 v5, v5, v5
	v_mul_f32_e32 v88, v4, v5
	v_mad_i64_i32 v[4:5], s[6:7], v76, s45, 0
	v_lshl_add_u32 v63, v59, 2, v74
	v_mul_u32_u24_e32 v64, 0x50, v59
	v_mad_i64_i32 v[4:5], s[6:7], s16, v127, v[4:5]
	v_mul_hi_u32_u24_e32 v58, 0x2400, v59
	v_mul_u32_u24_e32 v59, 0x2400, v59
	v_or_b32_e32 v5, v5, v58
	v_or_b32_e32 v4, v4, v59
	v_lshl_add_u64 v[4:5], v[4:5], 0, s[12:13]
	v_or_b32_e32 v58, v4, v61
	v_mov_b32_e32 v59, v5
	v_lshl_add_u64 v[94:95], s[2:3], 0, v[58:59]
	v_and_b32_e32 v58, 48, v3
	v_mov_b32_e32 v59, v2
	v_lshl_add_u64 v[4:5], v[4:5], 0, v[58:59]
	v_mov_b32_e32 v3, v2
	v_mov_b32_e32 v87, v86
	v_mov_b32_e32 v89, v88
	v_mov_b32_e32 v90, v80
	v_mov_b32_e32 v91, v78
	v_mov_b32_e32 v92, v78
	v_mov_b32_e32 v93, v80
	v_lshl_add_u64 v[96:97], s[10:11], 0, v[4:5]
	v_add_u32_e32 v128, v75, v64
	v_add_u32_e32 v129, v63, v60
	v_lshrrev_b32_e32 v185, 1, v60
	v_add_u32_e32 v185, v63, v185
	v_add_u32_e32 v130, v74, v62
	v_mov_b64_e32 v[98:99], v[2:3]
	s_branch .LBB0_347

.LBB0_347:
	v_cndmask_b32_e64 v3, 0, 1, s[22:23]
	v_cmp_ne_u32_e64 s[6:7], 1, v3
	s_andn2_b64 vcc, exec, s[22:23]
	s_cbranch_vccnz .LBB0_353
	s_mov_b32 exec_lo, -1
	s_mov_b32 exec_hi, 0
	global_load_dwordx4 v[186:189], v[84:85], off
	s_mov_b64 s[26:27], 0x24000
	v_lshl_add_u64 v[4:5], v[84:85], 0, s[26:27]
	global_load_dwordx4 v[190:193], v[4:5], off
	s_add_u32 s26, s26, 0x24000
	s_addc_u32 s27, s27, 0
	v_lshl_add_u64 v[4:5], v[84:85], 0, s[26:27]
	global_load_dwordx4 v[194:197], v[4:5], off
	s_add_u32 s26, s26, 0x24000
	s_addc_u32 s27, s27, 0
	v_lshl_add_u64 v[4:5], v[84:85], 0, s[26:27]
	global_load_dwordx4 v[198:201], v[4:5], off
	s_mov_b64 exec, -1
	v_mov_b32_e32 v3, v2
	ds_write2st64_b32 v77, v99, v98 offset1:1
	v_mov_b64_e32 v[98:99], v[2:3]
	s_waitcnt lgkmcnt(0)
	s_barrier
	s_and_saveexec_b64 s[22:23], s[8:9]
	s_cbranch_execz .LBB0_352
	v_mov_b32_e32 v98, 0
	s_mov_b64 s[24:25], 0
	v_mov_b32_e32 v3, v83
	v_mov_b32_e32 v4, v76
	v_mov_b32_e32 v99, v98
.LBB0_350:
	v_add_u32_e32 v5, 0xffffff00, v3
	ds_read_b32 v61, v5
	ds_read_b32 v60, v3
	v_pk_mul_f32 v[58:59], v[88:89], v[98:99] op_sel:[0,1] op_sel_hi:[1,0]
	v_add_u32_e32 v4, -1, v4
	v_pk_fma_f32 v[62:63], v[86:87], v[98:99], v[58:59]
	v_pk_fma_f32 v[58:59], v[86:87], v[98:99], v[58:59] neg_lo:[0,0,1] neg_hi:[0,0,1]
	v_cmp_eq_u32_e32 vcc, 0, v4
	v_mov_b32_e32 v63, v59
	v_add_u32_e32 v3, 0x200, v3
	s_or_b64 s[24:25], vcc, s[24:25]
	s_waitcnt lgkmcnt(0)
	v_pk_add_f32 v[98:99], v[62:63], v[60:61]
	s_andn2_b64 exec, exec, s[24:25]
	s_cbranch_execnz .LBB0_350
	s_or_b64 exec, exec, s[24:25]

.LBB0_353:
	s_and_b64 s[22:23], s[0:1], s[20:21]
	s_xor_b64 s[24:25], s[22:23], -1
	s_and_saveexec_b64 s[22:23], s[24:25]
	s_cbranch_execz .LBB0_346
	v_mbcnt_lo_u32_b32 v218, -1, 0
	v_mbcnt_hi_u32_b32 v218, -1, v218
	v_xor_b32_e32 v74, 0x80000000, v78
	v_and_b32_e32 v219, 15, v218
	v_lshrrev_b32_e32 v218, 5, v218
	v_lshl_add_u32 v218, v218, 4, v219
	v_lshlrev_b32_e32 v218, 2, v218
	s_mov_b64 s[24:25], 0
	s_and_b64 vcc, exec, s[6:7]
	s_waitcnt vmcnt(0)
	s_cbranch_vccnz .Ls5p_loop0
	s_mov_b32 vcc_lo, 0xffff0000
	s_mov_b32 vcc_hi, 0xffff0000
.Ls5p_loop1:
	s_cmp_lg_u32 s24, 0x1b0000
	s_cbranch_scc0 .Ls5p_nopf1
	s_add_u32 s26, s24, 0x90000
	s_addc_u32 s27, s25, 0
	s_mov_b64 exec, s[4:5]
	v_lshl_add_u64 v[4:5], v[84:85], 0, s[26:27]
	global_load_dwordx4 v[202:205], v[4:5], off
	s_add_u32 s26, s26, 0x24000
	s_addc_u32 s27, s27, 0
	v_lshl_add_u64 v[4:5], v[84:85], 0, s[26:27]
	global_load_dwordx4 v[206:209], v[4:5], off
	s_add_u32 s26, s26, 0x24000
	s_addc_u32 s27, s27, 0
	v_lshl_add_u64 v[4:5], v[84:85], 0, s[26:27]
	global_load_dwordx4 v[210:213], v[4:5], off
	s_add_u32 s26, s26, 0x24000
	s_addc_u32 s27, s27, 0
	v_lshl_add_u64 v[4:5], v[84:85], 0, s[26:27]
	global_load_dwordx4 v[214:217], v[4:5], off
	s_mov_b64 exec, -1
.Ls5p_nopf1:
	v_lshl_add_u64 v[4:5], v[94:95], 0, s[24:25]
	v_mfma_f32_16x16x32_bf16 v[66:69], v[186:189], v[10:13], 0
	v_mfma_f32_16x16x32_bf16 v[70:73], v[186:189], v[6:9], 0
	v_mfma_f32_16x16x32_bf16 v[102:105], v[186:189], v[18:21], 0
	v_mfma_f32_16x16x32_bf16 v[106:109], v[186:189], v[14:17], 0
	v_mfma_f32_16x16x32_bf16 v[110:113], v[186:189], v[26:29], 0
	v_mfma_f32_16x16x32_bf16 v[114:117], v[186:189], v[22:25], 0
	v_mfma_f32_16x16x32_bf16 v[132:135], v[186:189], v[34:37], 0
	v_mfma_f32_16x16x32_bf16 v[136:139], v[186:189], v[30:33], 0
	s_nop 0
	ds_write_b128 v128, v[66:69]
	ds_write_b128 v128, v[70:73] offset:1280
	ds_write_b128 v128, v[102:105] offset:2560
	ds_write_b128 v128, v[106:109] offset:3840
	ds_write_b128 v128, v[110:113] offset:5120
	ds_write_b128 v128, v[114:117] offset:6400
	ds_write_b128 v128, v[132:135] offset:7680
	ds_write_b128 v128, v[136:139] offset:8960
	ds_bpermute_b32 v58, v218, v186
	ds_bpermute_b32 v59, v218, v187
	ds_bpermute_b32 v60, v218, v188
	ds_bpermute_b32 v61, v218, v189
	s_waitcnt lgkmcnt(0)
	ds_read_b128 v[66:69], v130
	ds_read_b128 v[110:113], v130 offset:5120
	ds_read_b128 v[70:73], v130 offset:16
	ds_read_b128 v[114:117], v130 offset:5136
	ds_read_b128 v[102:105], v130 offset:32
	ds_read_b128 v[132:135], v130 offset:5152
	ds_read_b128 v[106:109], v130 offset:48
	ds_read_b128 v[136:139], v130 offset:5168
	v_cndmask_b32_e32 v100, v58, v60, vcc
	v_cndmask_b32_e32 v101, v59, v61, vcc
	s_waitcnt lgkmcnt(6)
	v_fmac_f32_e32 v66, v80, v99
	v_fmac_f32_e32 v110, v80, v98
	v_fmac_f32_e32 v66, v74, v98
	v_fmac_f32_e32 v110, v78, v99
	v_fmac_f32_e32 v67, v80, v66
	v_fmac_f32_e32 v111, v80, v110
	v_fmac_f32_e32 v67, v74, v110
	v_fmac_f32_e32 v111, v78, v66
	v_fmac_f32_e32 v68, v80, v67
	v_fmac_f32_e32 v112, v80, v111
	v_fmac_f32_e32 v68, v74, v111
	v_fmac_f32_e32 v112, v78, v67
	v_fmac_f32_e32 v69, v80, v68
	v_fmac_f32_e32 v113, v80, v112
	v_fmac_f32_e32 v69, v74, v112
	v_fmac_f32_e32 v113, v78, v68
	s_waitcnt lgkmcnt(4)
	v_fmac_f32_e32 v70, v80, v69
	v_fmac_f32_e32 v114, v80, v113
	v_fmac_f32_e32 v70, v74, v113
	v_fmac_f32_e32 v114, v78, v69
	v_cvt_pk_bf16_f32 v66, v66, v110
	v_cvt_pk_bf16_f32 v67, v67, v111
	v_cvt_pk_bf16_f32 v68, v68, v112
	v_cvt_pk_bf16_f32 v69, v69, v113
	ds_write_b128 v130, v[66:69]
	v_fmac_f32_e32 v71, v80, v70
	v_fmac_f32_e32 v115, v80, v114
	v_fmac_f32_e32 v71, v74, v114
	v_fmac_f32_e32 v115, v78, v70
	v_fmac_f32_e32 v72, v80, v71
	v_fmac_f32_e32 v116, v80, v115
	v_fmac_f32_e32 v72, v74, v115
	v_fmac_f32_e32 v116, v78, v71
	v_fmac_f32_e32 v73, v80, v72
	v_fmac_f32_e32 v117, v80, v116
	v_fmac_f32_e32 v73, v74, v116
	v_fmac_f32_e32 v117, v78, v72
	s_waitcnt lgkmcnt(3)
	v_fmac_f32_e32 v102, v80, v73
	v_fmac_f32_e32 v132, v80, v117
	v_fmac_f32_e32 v102, v74, v117
	v_fmac_f32_e32 v132, v78, v73
	v_cvt_pk_bf16_f32 v70, v70, v114
	v_cvt_pk_bf16_f32 v71, v71, v115
	v_cvt_pk_bf16_f32 v72, v72, v116
	v_cvt_pk_bf16_f32 v73, v73, v117
	ds_write_b128 v130, v[70:73] offset:16
	v_fmac_f32_e32 v103, v80, v102
	v_fmac_f32_e32 v133, v80, v132
	v_fmac_f32_e32 v103, v74, v132
	v_fmac_f32_e32 v133, v78, v102
	v_fmac_f32_e32 v104, v80, v103
	v_fmac_f32_e32 v134, v80, v133
	v_fmac_f32_e32 v104, v74, v133
	v_fmac_f32_e32 v134, v78, v103
	v_fmac_f32_e32 v105, v80, v104
	v_fmac_f32_e32 v135, v80, v134
	v_fmac_f32_e32 v105, v74, v134
	v_fmac_f32_e32 v135, v78, v104
	s_waitcnt lgkmcnt(2)
	v_fmac_f32_e32 v106, v80, v105
	v_fmac_f32_e32 v136, v80, v135
	v_fmac_f32_e32 v106, v74, v135
	v_fmac_f32_e32 v136, v78, v105
	v_cvt_pk_bf16_f32 v102, v102, v132
	v_cvt_pk_bf16_f32 v103, v103, v133
	v_cvt_pk_bf16_f32 v104, v104, v134
	v_cvt_pk_bf16_f32 v105, v105, v135
	ds_write_b128 v130, v[102:105] offset:32
	v_fmac_f32_e32 v107, v80, v106
	v_fmac_f32_e32 v137, v80, v136
	v_fmac_f32_e32 v107, v74, v136
	v_fmac_f32_e32 v137, v78, v106
	v_fmac_f32_e32 v108, v80, v107
	v_fmac_f32_e32 v138, v80, v137
	v_fmac_f32_e32 v108, v74, v137
	v_fmac_f32_e32 v138, v78, v107
	v_fmac_f32_e32 v109, v80, v108
	v_fmac_f32_e32 v139, v80, v138
	v_fmac_f32_e32 v109, v74, v138
	v_fmac_f32_e32 v139, v78, v108
	v_mov_b32_e32 v99, v109
	v_mov_b32_e32 v98, v139
	v_cvt_pk_bf16_f32 v106, v106, v136
	v_cvt_pk_bf16_f32 v107, v107, v137
	v_cvt_pk_bf16_f32 v108, v108, v138
	v_cvt_pk_bf16_f32 v109, v109, v139
	ds_write_b128 v130, v[106:109] offset:48
	s_waitcnt lgkmcnt(0)
	ds_read2_b32 v[66:67], v185 offset1:20
	ds_read2_b32 v[68:69], v185 offset0:40 offset1:60
	v_add_u32_e32 v3, 0x500, v185
	ds_read2_b32 v[102:103], v3 offset1:20
	ds_read2_b32 v[104:105], v3 offset0:40 offset1:60
	v_add_u32_e32 v3, 0xa00, v185
	ds_read2_b32 v[110:111], v3 offset1:20
	ds_read2_b32 v[112:113], v3 offset0:40 offset1:60
	v_add_u32_e32 v3, 0xf00, v185
	ds_read2_b32 v[132:133], v3 offset1:20
	ds_read2_b32 v[134:135], v3 offset0:40 offset1:60
	s_waitcnt lgkmcnt(6)
	v_mfma_f32_16x16x32_bf16 v[62:65], v[42:45], v[66:69], 0
	s_waitcnt lgkmcnt(4)
	v_mfma_f32_16x16x32_bf16 v[62:65], v[46:49], v[102:105], v[62:65]
	s_waitcnt lgkmcnt(2)
	v_mfma_f32_16x16x32_bf16 v[62:65], v[50:53], v[110:113], v[62:65]
	s_waitcnt lgkmcnt(0)
	v_lshlrev_b32_e32 v70, 16, v100
	v_and_b32_e32 v71, 0xffff0000, v100
	v_mfma_f32_16x16x32_bf16 v[62:65], v[54:57], v[132:135], v[62:65]
	v_lshlrev_b32_e32 v72, 16, v101
	v_and_b32_e32 v73, 0xffff0000, v101
	s_nop 7
	v_fmac_f32_e32 v62, v38, v70
	v_fmac_f32_e32 v63, v39, v71
	v_fmac_f32_e32 v64, v40, v72
	v_fmac_f32_e32 v65, v41, v73
	v_mul_f32_e32 v70, 0x3d372713, v62
	v_mul_f32_e32 v71, 0x3d372713, v63
	v_mul_f32_e32 v72, 0x3d372713, v64
	v_mul_f32_e32 v73, 0x3d372713, v65
	v_mul_f32_e32 v70, v62, v70
	v_mul_f32_e32 v71, v63, v71
	v_mul_f32_e32 v72, v64, v72
	v_mul_f32_e32 v73, v65, v73
	v_fma_f32 v70, v62, v70, v62
	v_fma_f32 v71, v63, v71, v63
	v_fma_f32 v72, v64, v72, v64
	v_fma_f32 v73, v65, v73, v65
	v_mul_f32_e32 v70, 0x3f4c422a, v70
	v_mul_f32_e32 v71, 0x3f4c422a, v71
	v_mul_f32_e32 v72, 0x3f4c422a, v72
	v_mul_f32_e32 v73, 0x3f4c422a, v73
	v_mul_f32_e32 v70, -2.0, v70
	v_mul_f32_e32 v71, -2.0, v71
	v_mul_f32_e32 v72, -2.0, v72
	v_mul_f32_e32 v73, -2.0, v73
	v_mul_f32_e32 v70, 0x3fb8aa3b, v70
	v_mul_f32_e32 v71, 0x3fb8aa3b, v71
	v_mul_f32_e32 v72, 0x3fb8aa3b, v72
	v_mul_f32_e32 v73, 0x3fb8aa3b, v73
	v_exp_f32_e32 v70, v70
	v_exp_f32_e32 v71, v71
	v_exp_f32_e32 v72, v72
	v_exp_f32_e32 v73, v73
	v_add_f32_e32 v70, 1.0, v70
	v_add_f32_e32 v71, 1.0, v71
	v_add_f32_e32 v72, 1.0, v72
	v_add_f32_e32 v73, 1.0, v73
	v_rcp_f32_e32 v70, v70
	v_rcp_f32_e32 v71, v71
	v_rcp_f32_e32 v72, v72
	v_rcp_f32_e32 v73, v73
	v_mul_f32_e32 v62, v62, v70
	v_mul_f32_e32 v63, v63, v71
	v_mul_f32_e32 v64, v64, v72
	v_mul_f32_e32 v65, v65, v73
	v_cvt_pk_bf16_f32 v62, v62, v63
	v_cvt_pk_bf16_f32 v63, v64, v65
	global_store_dwordx2 v[4:5], v[62:63], off
	s_add_u32 s26, s24, 0x24000
	s_addc_u32 s27, s25, 0
	v_lshl_add_u64 v[4:5], v[94:95], 0, s[26:27]
	v_mfma_f32_16x16x32_bf16 v[66:69], v[190:193], v[10:13], 0
	v_mfma_f32_16x16x32_bf16 v[70:73], v[190:193], v[6:9], 0
	v_mfma_f32_16x16x32_bf16 v[102:105], v[190:193], v[18:21], 0
	v_mfma_f32_16x16x32_bf16 v[106:109], v[190:193], v[14:17], 0
	v_mfma_f32_16x16x32_bf16 v[110:113], v[190:193], v[26:29], 0
	v_mfma_f32_16x16x32_bf16 v[114:117], v[190:193], v[22:25], 0
	v_mfma_f32_16x16x32_bf16 v[132:135], v[190:193], v[34:37], 0
	v_mfma_f32_16x16x32_bf16 v[136:139], v[190:193], v[30:33], 0
	s_nop 0
	ds_write_b128 v128, v[66:69]
	ds_write_b128 v128, v[70:73] offset:1280
	ds_write_b128 v128, v[102:105] offset:2560
	ds_write_b128 v128, v[106:109] offset:3840
	ds_write_b128 v128, v[110:113] offset:5120
	ds_write_b128 v128, v[114:117] offset:6400
	ds_write_b128 v128, v[132:135] offset:7680
	ds_write_b128 v128, v[136:139] offset:8960
	ds_bpermute_b32 v58, v218, v190
	ds_bpermute_b32 v59, v218, v191
	ds_bpermute_b32 v60, v218, v192
	ds_bpermute_b32 v61, v218, v193
	s_waitcnt lgkmcnt(0)
	ds_read_b128 v[66:69], v130
	ds_read_b128 v[110:113], v130 offset:5120
	ds_read_b128 v[70:73], v130 offset:16
	ds_read_b128 v[114:117], v130 offset:5136
	ds_read_b128 v[102:105], v130 offset:32
	ds_read_b128 v[132:135], v130 offset:5152
	ds_read_b128 v[106:109], v130 offset:48
	ds_read_b128 v[136:139], v130 offset:5168
	v_cndmask_b32_e32 v100, v58, v60, vcc
	v_cndmask_b32_e32 v101, v59, v61, vcc
	s_waitcnt lgkmcnt(6)
	v_fmac_f32_e32 v66, v80, v99
	v_fmac_f32_e32 v110, v80, v98
	v_fmac_f32_e32 v66, v74, v98
	v_fmac_f32_e32 v110, v78, v99
	v_fmac_f32_e32 v67, v80, v66
	v_fmac_f32_e32 v111, v80, v110
	v_fmac_f32_e32 v67, v74, v110
	v_fmac_f32_e32 v111, v78, v66
	v_fmac_f32_e32 v68, v80, v67
	v_fmac_f32_e32 v112, v80, v111
	v_fmac_f32_e32 v68, v74, v111
	v_fmac_f32_e32 v112, v78, v67
	v_fmac_f32_e32 v69, v80, v68
	v_fmac_f32_e32 v113, v80, v112
	v_fmac_f32_e32 v69, v74, v112
	v_fmac_f32_e32 v113, v78, v68
	s_waitcnt lgkmcnt(4)
	v_fmac_f32_e32 v70, v80, v69
	v_fmac_f32_e32 v114, v80, v113
	v_fmac_f32_e32 v70, v74, v113
	v_fmac_f32_e32 v114, v78, v69
	v_cvt_pk_bf16_f32 v66, v66, v110
	v_cvt_pk_bf16_f32 v67, v67, v111
	v_cvt_pk_bf16_f32 v68, v68, v112
	v_cvt_pk_bf16_f32 v69, v69, v113
	ds_write_b128 v130, v[66:69]
	v_fmac_f32_e32 v71, v80, v70
	v_fmac_f32_e32 v115, v80, v114
	v_fmac_f32_e32 v71, v74, v114
	v_fmac_f32_e32 v115, v78, v70
	v_fmac_f32_e32 v72, v80, v71
	v_fmac_f32_e32 v116, v80, v115
	v_fmac_f32_e32 v72, v74, v115
	v_fmac_f32_e32 v116, v78, v71
	v_fmac_f32_e32 v73, v80, v72
	v_fmac_f32_e32 v117, v80, v116
	v_fmac_f32_e32 v73, v74, v116
	v_fmac_f32_e32 v117, v78, v72
	s_waitcnt lgkmcnt(3)
	v_fmac_f32_e32 v102, v80, v73
	v_fmac_f32_e32 v132, v80, v117
	v_fmac_f32_e32 v102, v74, v117
	v_fmac_f32_e32 v132, v78, v73
	v_cvt_pk_bf16_f32 v70, v70, v114
	v_cvt_pk_bf16_f32 v71, v71, v115
	v_cvt_pk_bf16_f32 v72, v72, v116
	v_cvt_pk_bf16_f32 v73, v73, v117
	ds_write_b128 v130, v[70:73] offset:16
	v_fmac_f32_e32 v103, v80, v102
	v_fmac_f32_e32 v133, v80, v132
	v_fmac_f32_e32 v103, v74, v132
	v_fmac_f32_e32 v133, v78, v102
	v_fmac_f32_e32 v104, v80, v103
	v_fmac_f32_e32 v134, v80, v133
	v_fmac_f32_e32 v104, v74, v133
	v_fmac_f32_e32 v134, v78, v103
	v_fmac_f32_e32 v105, v80, v104
	v_fmac_f32_e32 v135, v80, v134
	v_fmac_f32_e32 v105, v74, v134
	v_fmac_f32_e32 v135, v78, v104
	s_waitcnt lgkmcnt(2)
	v_fmac_f32_e32 v106, v80, v105
	v_fmac_f32_e32 v136, v80, v135
	v_fmac_f32_e32 v106, v74, v135
	v_fmac_f32_e32 v136, v78, v105
	v_cvt_pk_bf16_f32 v102, v102, v132
	v_cvt_pk_bf16_f32 v103, v103, v133
	v_cvt_pk_bf16_f32 v104, v104, v134
	v_cvt_pk_bf16_f32 v105, v105, v135
	ds_write_b128 v130, v[102:105] offset:32
	v_fmac_f32_e32 v107, v80, v106
	v_fmac_f32_e32 v137, v80, v136
	v_fmac_f32_e32 v107, v74, v136
	v_fmac_f32_e32 v137, v78, v106
	v_fmac_f32_e32 v108, v80, v107
	v_fmac_f32_e32 v138, v80, v137
	v_fmac_f32_e32 v108, v74, v137
	v_fmac_f32_e32 v138, v78, v107
	v_fmac_f32_e32 v109, v80, v108
	v_fmac_f32_e32 v139, v80, v138
	v_fmac_f32_e32 v109, v74, v138
	v_fmac_f32_e32 v139, v78, v108
	v_mov_b32_e32 v99, v109
	v_mov_b32_e32 v98, v139
	v_cvt_pk_bf16_f32 v106, v106, v136
	v_cvt_pk_bf16_f32 v107, v107, v137
	v_cvt_pk_bf16_f32 v108, v108, v138
	v_cvt_pk_bf16_f32 v109, v109, v139
	ds_write_b128 v130, v[106:109] offset:48
	s_waitcnt lgkmcnt(0)
	ds_read2_b32 v[66:67], v185 offset1:20
	ds_read2_b32 v[68:69], v185 offset0:40 offset1:60
	v_add_u32_e32 v3, 0x500, v185
	ds_read2_b32 v[102:103], v3 offset1:20
	ds_read2_b32 v[104:105], v3 offset0:40 offset1:60
	v_add_u32_e32 v3, 0xa00, v185
	ds_read2_b32 v[110:111], v3 offset1:20
	ds_read2_b32 v[112:113], v3 offset0:40 offset1:60
	v_add_u32_e32 v3, 0xf00, v185
	ds_read2_b32 v[132:133], v3 offset1:20
	ds_read2_b32 v[134:135], v3 offset0:40 offset1:60
	s_waitcnt lgkmcnt(6)
	v_mfma_f32_16x16x32_bf16 v[62:65], v[42:45], v[66:69], 0
	s_waitcnt lgkmcnt(4)
	v_mfma_f32_16x16x32_bf16 v[62:65], v[46:49], v[102:105], v[62:65]
	s_waitcnt lgkmcnt(2)
	v_mfma_f32_16x16x32_bf16 v[62:65], v[50:53], v[110:113], v[62:65]
	s_waitcnt lgkmcnt(0)
	v_lshlrev_b32_e32 v70, 16, v100
	v_and_b32_e32 v71, 0xffff0000, v100
	v_mfma_f32_16x16x32_bf16 v[62:65], v[54:57], v[132:135], v[62:65]
	v_lshlrev_b32_e32 v72, 16, v101
	v_and_b32_e32 v73, 0xffff0000, v101
	s_nop 7
	v_fmac_f32_e32 v62, v38, v70
	v_fmac_f32_e32 v63, v39, v71
	v_fmac_f32_e32 v64, v40, v72
	v_fmac_f32_e32 v65, v41, v73
	v_mul_f32_e32 v70, 0x3d372713, v62
	v_mul_f32_e32 v71, 0x3d372713, v63
	v_mul_f32_e32 v72, 0x3d372713, v64
	v_mul_f32_e32 v73, 0x3d372713, v65
	v_mul_f32_e32 v70, v62, v70
	v_mul_f32_e32 v71, v63, v71
	v_mul_f32_e32 v72, v64, v72
	v_mul_f32_e32 v73, v65, v73
	v_fma_f32 v70, v62, v70, v62
	v_fma_f32 v71, v63, v71, v63
	v_fma_f32 v72, v64, v72, v64
	v_fma_f32 v73, v65, v73, v65
	v_mul_f32_e32 v70, 0x3f4c422a, v70
	v_mul_f32_e32 v71, 0x3f4c422a, v71
	v_mul_f32_e32 v72, 0x3f4c422a, v72
	v_mul_f32_e32 v73, 0x3f4c422a, v73
	v_mul_f32_e32 v70, -2.0, v70
	v_mul_f32_e32 v71, -2.0, v71
	v_mul_f32_e32 v72, -2.0, v72
	v_mul_f32_e32 v73, -2.0, v73
	v_mul_f32_e32 v70, 0x3fb8aa3b, v70
	v_mul_f32_e32 v71, 0x3fb8aa3b, v71
	v_mul_f32_e32 v72, 0x3fb8aa3b, v72
	v_mul_f32_e32 v73, 0x3fb8aa3b, v73
	v_exp_f32_e32 v70, v70
	v_exp_f32_e32 v71, v71
	v_exp_f32_e32 v72, v72
	v_exp_f32_e32 v73, v73
	v_add_f32_e32 v70, 1.0, v70
	v_add_f32_e32 v71, 1.0, v71
	v_add_f32_e32 v72, 1.0, v72
	v_add_f32_e32 v73, 1.0, v73
	v_rcp_f32_e32 v70, v70
	v_rcp_f32_e32 v71, v71
	v_rcp_f32_e32 v72, v72
	v_rcp_f32_e32 v73, v73
	v_mul_f32_e32 v62, v62, v70
	v_mul_f32_e32 v63, v63, v71
	v_mul_f32_e32 v64, v64, v72
	v_mul_f32_e32 v65, v65, v73
	v_cvt_pk_bf16_f32 v62, v62, v63
	v_cvt_pk_bf16_f32 v63, v64, v65
	global_store_dwordx2 v[4:5], v[62:63], off
	s_add_u32 s26, s24, 0x48000
	s_addc_u32 s27, s25, 0
	v_lshl_add_u64 v[4:5], v[94:95], 0, s[26:27]
	v_mfma_f32_16x16x32_bf16 v[66:69], v[194:197], v[10:13], 0
	v_mfma_f32_16x16x32_bf16 v[70:73], v[194:197], v[6:9], 0
	v_mfma_f32_16x16x32_bf16 v[102:105], v[194:197], v[18:21], 0
	v_mfma_f32_16x16x32_bf16 v[106:109], v[194:197], v[14:17], 0
	v_mfma_f32_16x16x32_bf16 v[110:113], v[194:197], v[26:29], 0
	v_mfma_f32_16x16x32_bf16 v[114:117], v[194:197], v[22:25], 0
	v_mfma_f32_16x16x32_bf16 v[132:135], v[194:197], v[34:37], 0
	v_mfma_f32_16x16x32_bf16 v[136:139], v[194:197], v[30:33], 0
	s_nop 0
	ds_write_b128 v128, v[66:69]
	ds_write_b128 v128, v[70:73] offset:1280
	ds_write_b128 v128, v[102:105] offset:2560
	ds_write_b128 v128, v[106:109] offset:3840
	ds_write_b128 v128, v[110:113] offset:5120
	ds_write_b128 v128, v[114:117] offset:6400
	ds_write_b128 v128, v[132:135] offset:7680
	ds_write_b128 v128, v[136:139] offset:8960
	ds_bpermute_b32 v58, v218, v194
	ds_bpermute_b32 v59, v218, v195
	ds_bpermute_b32 v60, v218, v196
	ds_bpermute_b32 v61, v218, v197
	s_waitcnt lgkmcnt(0)
	ds_read_b128 v[66:69], v130
	ds_read_b128 v[110:113], v130 offset:5120
	ds_read_b128 v[70:73], v130 offset:16
	ds_read_b128 v[114:117], v130 offset:5136
	ds_read_b128 v[102:105], v130 offset:32
	ds_read_b128 v[132:135], v130 offset:5152
	ds_read_b128 v[106:109], v130 offset:48
	ds_read_b128 v[136:139], v130 offset:5168
	v_cndmask_b32_e32 v100, v58, v60, vcc
	v_cndmask_b32_e32 v101, v59, v61, vcc
	s_waitcnt lgkmcnt(6)
	v_fmac_f32_e32 v66, v80, v99
	v_fmac_f32_e32 v110, v80, v98
	v_fmac_f32_e32 v66, v74, v98
	v_fmac_f32_e32 v110, v78, v99
	v_fmac_f32_e32 v67, v80, v66
	v_fmac_f32_e32 v111, v80, v110
	v_fmac_f32_e32 v67, v74, v110
	v_fmac_f32_e32 v111, v78, v66
	v_fmac_f32_e32 v68, v80, v67
	v_fmac_f32_e32 v112, v80, v111
	v_fmac_f32_e32 v68, v74, v111
	v_fmac_f32_e32 v112, v78, v67
	v_fmac_f32_e32 v69, v80, v68
	v_fmac_f32_e32 v113, v80, v112
	v_fmac_f32_e32 v69, v74, v112
	v_fmac_f32_e32 v113, v78, v68
	s_waitcnt lgkmcnt(4)
	v_fmac_f32_e32 v70, v80, v69
	v_fmac_f32_e32 v114, v80, v113
	v_fmac_f32_e32 v70, v74, v113
	v_fmac_f32_e32 v114, v78, v69
	v_cvt_pk_bf16_f32 v66, v66, v110
	v_cvt_pk_bf16_f32 v67, v67, v111
	v_cvt_pk_bf16_f32 v68, v68, v112
	v_cvt_pk_bf16_f32 v69, v69, v113
	ds_write_b128 v130, v[66:69]
	v_fmac_f32_e32 v71, v80, v70
	v_fmac_f32_e32 v115, v80, v114
	v_fmac_f32_e32 v71, v74, v114
	v_fmac_f32_e32 v115, v78, v70
	v_fmac_f32_e32 v72, v80, v71
	v_fmac_f32_e32 v116, v80, v115
	v_fmac_f32_e32 v72, v74, v115
	v_fmac_f32_e32 v116, v78, v71
	v_fmac_f32_e32 v73, v80, v72
	v_fmac_f32_e32 v117, v80, v116
	v_fmac_f32_e32 v73, v74, v116
	v_fmac_f32_e32 v117, v78, v72
	s_waitcnt lgkmcnt(3)
	v_fmac_f32_e32 v102, v80, v73
	v_fmac_f32_e32 v132, v80, v117
	v_fmac_f32_e32 v102, v74, v117
	v_fmac_f32_e32 v132, v78, v73
	v_cvt_pk_bf16_f32 v70, v70, v114
	v_cvt_pk_bf16_f32 v71, v71, v115
	v_cvt_pk_bf16_f32 v72, v72, v116
	v_cvt_pk_bf16_f32 v73, v73, v117
	ds_write_b128 v130, v[70:73] offset:16
	v_fmac_f32_e32 v103, v80, v102
	v_fmac_f32_e32 v133, v80, v132
	v_fmac_f32_e32 v103, v74, v132
	v_fmac_f32_e32 v133, v78, v102
	v_fmac_f32_e32 v104, v80, v103
	v_fmac_f32_e32 v134, v80, v133
	v_fmac_f32_e32 v104, v74, v133
	v_fmac_f32_e32 v134, v78, v103
	v_fmac_f32_e32 v105, v80, v104
	v_fmac_f32_e32 v135, v80, v134
	v_fmac_f32_e32 v105, v74, v134
	v_fmac_f32_e32 v135, v78, v104
	s_waitcnt lgkmcnt(2)
	v_fmac_f32_e32 v106, v80, v105
	v_fmac_f32_e32 v136, v80, v135
	v_fmac_f32_e32 v106, v74, v135
	v_fmac_f32_e32 v136, v78, v105
	v_cvt_pk_bf16_f32 v102, v102, v132
	v_cvt_pk_bf16_f32 v103, v103, v133
	v_cvt_pk_bf16_f32 v104, v104, v134
	v_cvt_pk_bf16_f32 v105, v105, v135
	ds_write_b128 v130, v[102:105] offset:32
	v_fmac_f32_e32 v107, v80, v106
	v_fmac_f32_e32 v137, v80, v136
	v_fmac_f32_e32 v107, v74, v136
	v_fmac_f32_e32 v137, v78, v106
	v_fmac_f32_e32 v108, v80, v107
	v_fmac_f32_e32 v138, v80, v137
	v_fmac_f32_e32 v108, v74, v137
	v_fmac_f32_e32 v138, v78, v107
	v_fmac_f32_e32 v109, v80, v108
	v_fmac_f32_e32 v139, v80, v138
	v_fmac_f32_e32 v109, v74, v138
	v_fmac_f32_e32 v139, v78, v108
	v_mov_b32_e32 v99, v109
	v_mov_b32_e32 v98, v139
	v_cvt_pk_bf16_f32 v106, v106, v136
	v_cvt_pk_bf16_f32 v107, v107, v137
	v_cvt_pk_bf16_f32 v108, v108, v138
	v_cvt_pk_bf16_f32 v109, v109, v139
	ds_write_b128 v130, v[106:109] offset:48
	s_waitcnt lgkmcnt(0)
	ds_read2_b32 v[66:67], v185 offset1:20
	ds_read2_b32 v[68:69], v185 offset0:40 offset1:60
	v_add_u32_e32 v3, 0x500, v185
	ds_read2_b32 v[102:103], v3 offset1:20
	ds_read2_b32 v[104:105], v3 offset0:40 offset1:60
	v_add_u32_e32 v3, 0xa00, v185
	ds_read2_b32 v[110:111], v3 offset1:20
	ds_read2_b32 v[112:113], v3 offset0:40 offset1:60
	v_add_u32_e32 v3, 0xf00, v185
	ds_read2_b32 v[132:133], v3 offset1:20
	ds_read2_b32 v[134:135], v3 offset0:40 offset1:60
	s_waitcnt lgkmcnt(6)
	v_mfma_f32_16x16x32_bf16 v[62:65], v[42:45], v[66:69], 0
	s_waitcnt lgkmcnt(4)
	v_mfma_f32_16x16x32_bf16 v[62:65], v[46:49], v[102:105], v[62:65]
	s_waitcnt lgkmcnt(2)
	v_mfma_f32_16x16x32_bf16 v[62:65], v[50:53], v[110:113], v[62:65]
	s_waitcnt lgkmcnt(0)
	v_lshlrev_b32_e32 v70, 16, v100
	v_and_b32_e32 v71, 0xffff0000, v100
	v_mfma_f32_16x16x32_bf16 v[62:65], v[54:57], v[132:135], v[62:65]
	v_lshlrev_b32_e32 v72, 16, v101
	v_and_b32_e32 v73, 0xffff0000, v101
	s_nop 7
	v_fmac_f32_e32 v62, v38, v70
	v_fmac_f32_e32 v63, v39, v71
	v_fmac_f32_e32 v64, v40, v72
	v_fmac_f32_e32 v65, v41, v73
	v_mul_f32_e32 v70, 0x3d372713, v62
	v_mul_f32_e32 v71, 0x3d372713, v63
	v_mul_f32_e32 v72, 0x3d372713, v64
	v_mul_f32_e32 v73, 0x3d372713, v65
	v_mul_f32_e32 v70, v62, v70
	v_mul_f32_e32 v71, v63, v71
	v_mul_f32_e32 v72, v64, v72
	v_mul_f32_e32 v73, v65, v73
	v_fma_f32 v70, v62, v70, v62
	v_fma_f32 v71, v63, v71, v63
	v_fma_f32 v72, v64, v72, v64
	v_fma_f32 v73, v65, v73, v65
	v_mul_f32_e32 v70, 0x3f4c422a, v70
	v_mul_f32_e32 v71, 0x3f4c422a, v71
	v_mul_f32_e32 v72, 0x3f4c422a, v72
	v_mul_f32_e32 v73, 0x3f4c422a, v73
	v_mul_f32_e32 v70, -2.0, v70
	v_mul_f32_e32 v71, -2.0, v71
	v_mul_f32_e32 v72, -2.0, v72
	v_mul_f32_e32 v73, -2.0, v73
	v_mul_f32_e32 v70, 0x3fb8aa3b, v70
	v_mul_f32_e32 v71, 0x3fb8aa3b, v71
	v_mul_f32_e32 v72, 0x3fb8aa3b, v72
	v_mul_f32_e32 v73, 0x3fb8aa3b, v73
	v_exp_f32_e32 v70, v70
	v_exp_f32_e32 v71, v71
	v_exp_f32_e32 v72, v72
	v_exp_f32_e32 v73, v73
	v_add_f32_e32 v70, 1.0, v70
	v_add_f32_e32 v71, 1.0, v71
	v_add_f32_e32 v72, 1.0, v72
	v_add_f32_e32 v73, 1.0, v73
	v_rcp_f32_e32 v70, v70
	v_rcp_f32_e32 v71, v71
	v_rcp_f32_e32 v72, v72
	v_rcp_f32_e32 v73, v73
	v_mul_f32_e32 v62, v62, v70
	v_mul_f32_e32 v63, v63, v71
	v_mul_f32_e32 v64, v64, v72
	v_mul_f32_e32 v65, v65, v73
	v_cvt_pk_bf16_f32 v62, v62, v63
	v_cvt_pk_bf16_f32 v63, v64, v65
	global_store_dwordx2 v[4:5], v[62:63], off
	s_add_u32 s26, s24, 0x6c000
	s_addc_u32 s27, s25, 0
	v_lshl_add_u64 v[4:5], v[94:95], 0, s[26:27]
	v_mfma_f32_16x16x32_bf16 v[66:69], v[198:201], v[10:13], 0
	v_mfma_f32_16x16x32_bf16 v[70:73], v[198:201], v[6:9], 0
	v_mfma_f32_16x16x32_bf16 v[102:105], v[198:201], v[18:21], 0
	v_mfma_f32_16x16x32_bf16 v[106:109], v[198:201], v[14:17], 0
	v_mfma_f32_16x16x32_bf16 v[110:113], v[198:201], v[26:29], 0
	v_mfma_f32_16x16x32_bf16 v[114:117], v[198:201], v[22:25], 0
	v_mfma_f32_16x16x32_bf16 v[132:135], v[198:201], v[34:37], 0
	v_mfma_f32_16x16x32_bf16 v[136:139], v[198:201], v[30:33], 0
	s_nop 0
	ds_write_b128 v128, v[66:69]
	ds_write_b128 v128, v[70:73] offset:1280
	ds_write_b128 v128, v[102:105] offset:2560
	ds_write_b128 v128, v[106:109] offset:3840
	ds_write_b128 v128, v[110:113] offset:5120
	ds_write_b128 v128, v[114:117] offset:6400
	ds_write_b128 v128, v[132:135] offset:7680
	ds_write_b128 v128, v[136:139] offset:8960
	ds_bpermute_b32 v58, v218, v198
	ds_bpermute_b32 v59, v218, v199
	ds_bpermute_b32 v60, v218, v200
	ds_bpermute_b32 v61, v218, v201
	s_waitcnt lgkmcnt(0)
	ds_read_b128 v[66:69], v130
	ds_read_b128 v[110:113], v130 offset:5120
	ds_read_b128 v[70:73], v130 offset:16
	ds_read_b128 v[114:117], v130 offset:5136
	ds_read_b128 v[102:105], v130 offset:32
	ds_read_b128 v[132:135], v130 offset:5152
	ds_read_b128 v[106:109], v130 offset:48
	ds_read_b128 v[136:139], v130 offset:5168
	v_cndmask_b32_e32 v100, v58, v60, vcc
	v_cndmask_b32_e32 v101, v59, v61, vcc
	s_waitcnt lgkmcnt(6)
	v_fmac_f32_e32 v66, v80, v99
	v_fmac_f32_e32 v110, v80, v98
	v_fmac_f32_e32 v66, v74, v98
	v_fmac_f32_e32 v110, v78, v99
	v_fmac_f32_e32 v67, v80, v66
	v_fmac_f32_e32 v111, v80, v110
	v_fmac_f32_e32 v67, v74, v110
	v_fmac_f32_e32 v111, v78, v66
	v_fmac_f32_e32 v68, v80, v67
	v_fmac_f32_e32 v112, v80, v111
	v_fmac_f32_e32 v68, v74, v111
	v_fmac_f32_e32 v112, v78, v67
	v_fmac_f32_e32 v69, v80, v68
	v_fmac_f32_e32 v113, v80, v112
	v_fmac_f32_e32 v69, v74, v112
	v_fmac_f32_e32 v113, v78, v68
	s_waitcnt lgkmcnt(4)
	v_fmac_f32_e32 v70, v80, v69
	v_fmac_f32_e32 v114, v80, v113
	v_fmac_f32_e32 v70, v74, v113
	v_fmac_f32_e32 v114, v78, v69
	v_cvt_pk_bf16_f32 v66, v66, v110
	v_cvt_pk_bf16_f32 v67, v67, v111
	v_cvt_pk_bf16_f32 v68, v68, v112
	v_cvt_pk_bf16_f32 v69, v69, v113
	ds_write_b128 v130, v[66:69]
	v_fmac_f32_e32 v71, v80, v70
	v_fmac_f32_e32 v115, v80, v114
	v_fmac_f32_e32 v71, v74, v114
	v_fmac_f32_e32 v115, v78, v70
	v_fmac_f32_e32 v72, v80, v71
	v_fmac_f32_e32 v116, v80, v115
	v_fmac_f32_e32 v72, v74, v115
	v_fmac_f32_e32 v116, v78, v71
	v_fmac_f32_e32 v73, v80, v72
	v_fmac_f32_e32 v117, v80, v116
	v_fmac_f32_e32 v73, v74, v116
	v_fmac_f32_e32 v117, v78, v72
	s_waitcnt lgkmcnt(3)
	v_fmac_f32_e32 v102, v80, v73
	v_fmac_f32_e32 v132, v80, v117
	v_fmac_f32_e32 v102, v74, v117
	v_fmac_f32_e32 v132, v78, v73
	v_cvt_pk_bf16_f32 v70, v70, v114
	v_cvt_pk_bf16_f32 v71, v71, v115
	v_cvt_pk_bf16_f32 v72, v72, v116
	v_cvt_pk_bf16_f32 v73, v73, v117
	ds_write_b128 v130, v[70:73] offset:16
	v_fmac_f32_e32 v103, v80, v102
	v_fmac_f32_e32 v133, v80, v132
	v_fmac_f32_e32 v103, v74, v132
	v_fmac_f32_e32 v133, v78, v102
	v_fmac_f32_e32 v104, v80, v103
	v_fmac_f32_e32 v134, v80, v133
	v_fmac_f32_e32 v104, v74, v133
	v_fmac_f32_e32 v134, v78, v103
	v_fmac_f32_e32 v105, v80, v104
	v_fmac_f32_e32 v135, v80, v134
	v_fmac_f32_e32 v105, v74, v134
	v_fmac_f32_e32 v135, v78, v104
	s_waitcnt lgkmcnt(2)
	v_fmac_f32_e32 v106, v80, v105
	v_fmac_f32_e32 v136, v80, v135
	v_fmac_f32_e32 v106, v74, v135
	v_fmac_f32_e32 v136, v78, v105
	v_cvt_pk_bf16_f32 v102, v102, v132
	v_cvt_pk_bf16_f32 v103, v103, v133
	v_cvt_pk_bf16_f32 v104, v104, v134
	v_cvt_pk_bf16_f32 v105, v105, v135
	ds_write_b128 v130, v[102:105] offset:32
	v_fmac_f32_e32 v107, v80, v106
	v_fmac_f32_e32 v137, v80, v136
	v_fmac_f32_e32 v107, v74, v136
	v_fmac_f32_e32 v137, v78, v106
	v_fmac_f32_e32 v108, v80, v107
	v_fmac_f32_e32 v138, v80, v137
	v_fmac_f32_e32 v108, v74, v137
	v_fmac_f32_e32 v138, v78, v107
	v_fmac_f32_e32 v109, v80, v108
	v_fmac_f32_e32 v139, v80, v138
	v_fmac_f32_e32 v109, v74, v138
	v_fmac_f32_e32 v139, v78, v108
	v_mov_b32_e32 v99, v109
	v_mov_b32_e32 v98, v139
	v_cvt_pk_bf16_f32 v106, v106, v136
	v_cvt_pk_bf16_f32 v107, v107, v137
	v_cvt_pk_bf16_f32 v108, v108, v138
	v_cvt_pk_bf16_f32 v109, v109, v139
	ds_write_b128 v130, v[106:109] offset:48
	s_waitcnt lgkmcnt(0)
	ds_read2_b32 v[66:67], v185 offset1:20
	ds_read2_b32 v[68:69], v185 offset0:40 offset1:60
	v_add_u32_e32 v3, 0x500, v185
	ds_read2_b32 v[102:103], v3 offset1:20
	ds_read2_b32 v[104:105], v3 offset0:40 offset1:60
	v_add_u32_e32 v3, 0xa00, v185
	ds_read2_b32 v[110:111], v3 offset1:20
	ds_read2_b32 v[112:113], v3 offset0:40 offset1:60
	v_add_u32_e32 v3, 0xf00, v185
	ds_read2_b32 v[132:133], v3 offset1:20
	ds_read2_b32 v[134:135], v3 offset0:40 offset1:60
	s_waitcnt lgkmcnt(6)
	v_mfma_f32_16x16x32_bf16 v[62:65], v[42:45], v[66:69], 0
	s_waitcnt lgkmcnt(4)
	v_mfma_f32_16x16x32_bf16 v[62:65], v[46:49], v[102:105], v[62:65]
	s_waitcnt lgkmcnt(2)
	v_mfma_f32_16x16x32_bf16 v[62:65], v[50:53], v[110:113], v[62:65]
	s_waitcnt lgkmcnt(0)
	v_lshlrev_b32_e32 v70, 16, v100
	v_and_b32_e32 v71, 0xffff0000, v100
	v_mfma_f32_16x16x32_bf16 v[62:65], v[54:57], v[132:135], v[62:65]
	v_lshlrev_b32_e32 v72, 16, v101
	v_and_b32_e32 v73, 0xffff0000, v101
	s_nop 7
	v_fmac_f32_e32 v62, v38, v70
	v_fmac_f32_e32 v63, v39, v71
	v_fmac_f32_e32 v64, v40, v72
	v_fmac_f32_e32 v65, v41, v73
	v_mul_f32_e32 v70, 0x3d372713, v62
	v_mul_f32_e32 v71, 0x3d372713, v63
	v_mul_f32_e32 v72, 0x3d372713, v64
	v_mul_f32_e32 v73, 0x3d372713, v65
	v_mul_f32_e32 v70, v62, v70
	v_mul_f32_e32 v71, v63, v71
	v_mul_f32_e32 v72, v64, v72
	v_mul_f32_e32 v73, v65, v73
	v_fma_f32 v70, v62, v70, v62
	v_fma_f32 v71, v63, v71, v63
	v_fma_f32 v72, v64, v72, v64
	v_fma_f32 v73, v65, v73, v65
	v_mul_f32_e32 v70, 0x3f4c422a, v70
	v_mul_f32_e32 v71, 0x3f4c422a, v71
	v_mul_f32_e32 v72, 0x3f4c422a, v72
	v_mul_f32_e32 v73, 0x3f4c422a, v73
	v_mul_f32_e32 v70, -2.0, v70
	v_mul_f32_e32 v71, -2.0, v71
	v_mul_f32_e32 v72, -2.0, v72
	v_mul_f32_e32 v73, -2.0, v73
	v_mul_f32_e32 v70, 0x3fb8aa3b, v70
	v_mul_f32_e32 v71, 0x3fb8aa3b, v71
	v_mul_f32_e32 v72, 0x3fb8aa3b, v72
	v_mul_f32_e32 v73, 0x3fb8aa3b, v73
	v_exp_f32_e32 v70, v70
	v_exp_f32_e32 v71, v71
	v_exp_f32_e32 v72, v72
	v_exp_f32_e32 v73, v73
	v_add_f32_e32 v70, 1.0, v70
	v_add_f32_e32 v71, 1.0, v71
	v_add_f32_e32 v72, 1.0, v72
	v_add_f32_e32 v73, 1.0, v73
	v_rcp_f32_e32 v70, v70
	v_rcp_f32_e32 v71, v71
	v_rcp_f32_e32 v72, v72
	v_rcp_f32_e32 v73, v73
	v_mul_f32_e32 v62, v62, v70
	v_mul_f32_e32 v63, v63, v71
	v_mul_f32_e32 v64, v64, v72
	v_mul_f32_e32 v65, v65, v73
	v_cvt_pk_bf16_f32 v62, v62, v63
	v_cvt_pk_bf16_f32 v63, v64, v65
	global_store_dwordx2 v[4:5], v[62:63], off
	s_add_u32 s24, s24, 0x90000
	s_addc_u32 s25, s25, 0
	s_cmp_lg_u32 s24, 0x240000
	s_cbranch_scc0 .LBB0_346
	s_waitcnt vmcnt(4)
	v_mov_b64_e32 v[186:187], v[202:203]
	v_mov_b64_e32 v[188:189], v[204:205]
	v_mov_b64_e32 v[190:191], v[206:207]
	v_mov_b64_e32 v[192:193], v[208:209]
	v_mov_b64_e32 v[194:195], v[210:211]
	v_mov_b64_e32 v[196:197], v[212:213]
	v_mov_b64_e32 v[198:199], v[214:215]
	v_mov_b64_e32 v[200:201], v[216:217]
	s_branch .Ls5p_loop1

.Ls5p_nopf0:
	v_mfma_f32_16x16x32_bf16 v[66:69], v[186:189], v[10:13], 0
	v_mfma_f32_16x16x32_bf16 v[70:73], v[186:189], v[6:9], 0
	v_mfma_f32_16x16x32_bf16 v[102:105], v[186:189], v[18:21], 0
	v_mfma_f32_16x16x32_bf16 v[106:109], v[186:189], v[14:17], 0
	v_mfma_f32_16x16x32_bf16 v[110:113], v[186:189], v[26:29], 0
	v_mfma_f32_16x16x32_bf16 v[114:117], v[186:189], v[22:25], 0
	v_mfma_f32_16x16x32_bf16 v[132:135], v[186:189], v[34:37], 0
	v_mfma_f32_16x16x32_bf16 v[136:139], v[186:189], v[30:33], 0
	s_nop 0
	ds_write_b128 v128, v[66:69]
	ds_write_b128 v128, v[70:73] offset:1280
	ds_write_b128 v128, v[102:105] offset:2560
	ds_write_b128 v128, v[106:109] offset:3840
	ds_write_b128 v128, v[110:113] offset:5120
	ds_write_b128 v128, v[114:117] offset:6400
	ds_write_b128 v128, v[132:135] offset:7680
	ds_write_b128 v128, v[136:139] offset:8960
	s_waitcnt lgkmcnt(0)
	ds_read_b128 v[66:69], v130
	ds_read_b128 v[110:113], v130 offset:5120
	ds_read_b128 v[70:73], v130 offset:16
	ds_read_b128 v[114:117], v130 offset:5136
	ds_read_b128 v[102:105], v130 offset:32
	ds_read_b128 v[132:135], v130 offset:5152
	ds_read_b128 v[106:109], v130 offset:48
	ds_read_b128 v[136:139], v130 offset:5168
	s_waitcnt lgkmcnt(6)
	v_fmac_f32_e32 v66, v80, v99
	v_fmac_f32_e32 v110, v80, v98
	v_fmac_f32_e32 v66, v74, v98
	v_fmac_f32_e32 v110, v78, v99
	v_fmac_f32_e32 v67, v80, v66
	v_fmac_f32_e32 v111, v80, v110
	v_fmac_f32_e32 v67, v74, v110
	v_fmac_f32_e32 v111, v78, v66
	v_fmac_f32_e32 v68, v80, v67
	v_fmac_f32_e32 v112, v80, v111
	v_fmac_f32_e32 v68, v74, v111
	v_fmac_f32_e32 v112, v78, v67
	v_fmac_f32_e32 v69, v80, v68
	v_fmac_f32_e32 v113, v80, v112
	v_fmac_f32_e32 v69, v74, v112
	v_fmac_f32_e32 v113, v78, v68
	s_waitcnt lgkmcnt(4)
	v_fmac_f32_e32 v70, v80, v69
	v_fmac_f32_e32 v114, v80, v113
	v_fmac_f32_e32 v70, v74, v113
	v_fmac_f32_e32 v114, v78, v69
	v_fmac_f32_e32 v71, v80, v70
	v_fmac_f32_e32 v115, v80, v114
	v_fmac_f32_e32 v71, v74, v114
	v_fmac_f32_e32 v115, v78, v70
	v_fmac_f32_e32 v72, v80, v71
	v_fmac_f32_e32 v116, v80, v115
	v_fmac_f32_e32 v72, v74, v115
	v_fmac_f32_e32 v116, v78, v71
	v_fmac_f32_e32 v73, v80, v72
	v_fmac_f32_e32 v117, v80, v116
	v_fmac_f32_e32 v73, v74, v116
	v_fmac_f32_e32 v117, v78, v72
	s_waitcnt lgkmcnt(2)
	v_fmac_f32_e32 v102, v80, v73
	v_fmac_f32_e32 v132, v80, v117
	v_fmac_f32_e32 v102, v74, v117
	v_fmac_f32_e32 v132, v78, v73
	v_fmac_f32_e32 v103, v80, v102
	v_fmac_f32_e32 v133, v80, v132
	v_fmac_f32_e32 v103, v74, v132
	v_fmac_f32_e32 v133, v78, v102
	v_fmac_f32_e32 v104, v80, v103
	v_fmac_f32_e32 v134, v80, v133
	v_fmac_f32_e32 v104, v74, v133
	v_fmac_f32_e32 v134, v78, v103
	v_fmac_f32_e32 v105, v80, v104
	v_fmac_f32_e32 v135, v80, v134
	v_fmac_f32_e32 v105, v74, v134
	v_fmac_f32_e32 v135, v78, v104
	s_waitcnt lgkmcnt(0)
	v_fmac_f32_e32 v106, v80, v105
	v_fmac_f32_e32 v136, v80, v135
	v_fmac_f32_e32 v106, v74, v135
	v_fmac_f32_e32 v136, v78, v105
	v_fmac_f32_e32 v107, v80, v106
	v_fmac_f32_e32 v137, v80, v136
	v_fmac_f32_e32 v107, v74, v136
	v_fmac_f32_e32 v137, v78, v106
	v_fmac_f32_e32 v108, v80, v107
	v_fmac_f32_e32 v138, v80, v137
	v_fmac_f32_e32 v108, v74, v137
	v_fmac_f32_e32 v138, v78, v107
	v_fmac_f32_e32 v109, v80, v108
	v_fmac_f32_e32 v139, v80, v138
	v_fmac_f32_e32 v109, v74, v138
	v_fmac_f32_e32 v139, v78, v108
	v_mov_b32_e32 v99, v109
	v_mov_b32_e32 v98, v139
	v_mfma_f32_16x16x32_bf16 v[66:69], v[190:193], v[10:13], 0
	v_mfma_f32_16x16x32_bf16 v[70:73], v[190:193], v[6:9], 0
	v_mfma_f32_16x16x32_bf16 v[102:105], v[190:193], v[18:21], 0
	v_mfma_f32_16x16x32_bf16 v[106:109], v[190:193], v[14:17], 0
	v_mfma_f32_16x16x32_bf16 v[110:113], v[190:193], v[26:29], 0
	v_mfma_f32_16x16x32_bf16 v[114:117], v[190:193], v[22:25], 0
	v_mfma_f32_16x16x32_bf16 v[132:135], v[190:193], v[34:37], 0
	v_mfma_f32_16x16x32_bf16 v[136:139], v[190:193], v[30:33], 0
	s_nop 0
	ds_write_b128 v128, v[66:69]
	ds_write_b128 v128, v[70:73] offset:1280
	ds_write_b128 v128, v[102:105] offset:2560
	ds_write_b128 v128, v[106:109] offset:3840
	ds_write_b128 v128, v[110:113] offset:5120
	ds_write_b128 v128, v[114:117] offset:6400
	ds_write_b128 v128, v[132:135] offset:7680
	ds_write_b128 v128, v[136:139] offset:8960
	s_waitcnt lgkmcnt(0)
	ds_read_b128 v[66:69], v130
	ds_read_b128 v[110:113], v130 offset:5120
	ds_read_b128 v[70:73], v130 offset:16
	ds_read_b128 v[114:117], v130 offset:5136
	ds_read_b128 v[102:105], v130 offset:32
	ds_read_b128 v[132:135], v130 offset:5152
	ds_read_b128 v[106:109], v130 offset:48
	ds_read_b128 v[136:139], v130 offset:5168
	s_waitcnt lgkmcnt(6)
	v_fmac_f32_e32 v66, v80, v99
	v_fmac_f32_e32 v110, v80, v98
	v_fmac_f32_e32 v66, v74, v98
	v_fmac_f32_e32 v110, v78, v99
	v_fmac_f32_e32 v67, v80, v66
	v_fmac_f32_e32 v111, v80, v110
	v_fmac_f32_e32 v67, v74, v110
	v_fmac_f32_e32 v111, v78, v66
	v_fmac_f32_e32 v68, v80, v67
	v_fmac_f32_e32 v112, v80, v111
	v_fmac_f32_e32 v68, v74, v111
	v_fmac_f32_e32 v112, v78, v67
	v_fmac_f32_e32 v69, v80, v68
	v_fmac_f32_e32 v113, v80, v112
	v_fmac_f32_e32 v69, v74, v112
	v_fmac_f32_e32 v113, v78, v68
	s_waitcnt lgkmcnt(4)
	v_fmac_f32_e32 v70, v80, v69
	v_fmac_f32_e32 v114, v80, v113
	v_fmac_f32_e32 v70, v74, v113
	v_fmac_f32_e32 v114, v78, v69
	v_fmac_f32_e32 v71, v80, v70
	v_fmac_f32_e32 v115, v80, v114
	v_fmac_f32_e32 v71, v74, v114
	v_fmac_f32_e32 v115, v78, v70
	v_fmac_f32_e32 v72, v80, v71
	v_fmac_f32_e32 v116, v80, v115
	v_fmac_f32_e32 v72, v74, v115
	v_fmac_f32_e32 v116, v78, v71
	v_fmac_f32_e32 v73, v80, v72
	v_fmac_f32_e32 v117, v80, v116
	v_fmac_f32_e32 v73, v74, v116
	v_fmac_f32_e32 v117, v78, v72
	s_waitcnt lgkmcnt(2)
	v_fmac_f32_e32 v102, v80, v73
	v_fmac_f32_e32 v132, v80, v117
	v_fmac_f32_e32 v102, v74, v117
	v_fmac_f32_e32 v132, v78, v73
	v_fmac_f32_e32 v103, v80, v102
	v_fmac_f32_e32 v133, v80, v132
	v_fmac_f32_e32 v103, v74, v132
	v_fmac_f32_e32 v133, v78, v102
	v_fmac_f32_e32 v104, v80, v103
	v_fmac_f32_e32 v134, v80, v133
	v_fmac_f32_e32 v104, v74, v133
	v_fmac_f32_e32 v134, v78, v103
	v_fmac_f32_e32 v105, v80, v104
	v_fmac_f32_e32 v135, v80, v134
	v_fmac_f32_e32 v105, v74, v134
	v_fmac_f32_e32 v135, v78, v104
	s_waitcnt lgkmcnt(0)
	v_fmac_f32_e32 v106, v80, v105
	v_fmac_f32_e32 v136, v80, v135
	v_fmac_f32_e32 v106, v74, v135
	v_fmac_f32_e32 v136, v78, v105
	v_fmac_f32_e32 v107, v80, v106
	v_fmac_f32_e32 v137, v80, v136
	v_fmac_f32_e32 v107, v74, v136
	v_fmac_f32_e32 v137, v78, v106
	v_fmac_f32_e32 v108, v80, v107
	v_fmac_f32_e32 v138, v80, v137
	v_fmac_f32_e32 v108, v74, v137
	v_fmac_f32_e32 v138, v78, v107
	v_fmac_f32_e32 v109, v80, v108
	v_fmac_f32_e32 v139, v80, v138
	v_fmac_f32_e32 v109, v74, v138
	v_fmac_f32_e32 v139, v78, v108
	v_mov_b32_e32 v99, v109
	v_mov_b32_e32 v98, v139
	v_mfma_f32_16x16x32_bf16 v[66:69], v[194:197], v[10:13], 0
	v_mfma_f32_16x16x32_bf16 v[70:73], v[194:197], v[6:9], 0
	v_mfma_f32_16x16x32_bf16 v[102:105], v[194:197], v[18:21], 0
	v_mfma_f32_16x16x32_bf16 v[106:109], v[194:197], v[14:17], 0
	v_mfma_f32_16x16x32_bf16 v[110:113], v[194:197], v[26:29], 0
	v_mfma_f32_16x16x32_bf16 v[114:117], v[194:197], v[22:25], 0
	v_mfma_f32_16x16x32_bf16 v[132:135], v[194:197], v[34:37], 0
	v_mfma_f32_16x16x32_bf16 v[136:139], v[194:197], v[30:33], 0
	s_nop 0
	ds_write_b128 v128, v[66:69]
	ds_write_b128 v128, v[70:73] offset:1280
	ds_write_b128 v128, v[102:105] offset:2560
	ds_write_b128 v128, v[106:109] offset:3840
	ds_write_b128 v128, v[110:113] offset:5120
	ds_write_b128 v128, v[114:117] offset:6400
	ds_write_b128 v128, v[132:135] offset:7680
	ds_write_b128 v128, v[136:139] offset:8960
	s_waitcnt lgkmcnt(0)
	ds_read_b128 v[66:69], v130
	ds_read_b128 v[110:113], v130 offset:5120
	ds_read_b128 v[70:73], v130 offset:16
	ds_read_b128 v[114:117], v130 offset:5136
	ds_read_b128 v[102:105], v130 offset:32
	ds_read_b128 v[132:135], v130 offset:5152
	ds_read_b128 v[106:109], v130 offset:48
	ds_read_b128 v[136:139], v130 offset:5168
	s_waitcnt lgkmcnt(6)
	v_fmac_f32_e32 v66, v80, v99
	v_fmac_f32_e32 v110, v80, v98
	v_fmac_f32_e32 v66, v74, v98
	v_fmac_f32_e32 v110, v78, v99
	v_fmac_f32_e32 v67, v80, v66
	v_fmac_f32_e32 v111, v80, v110
	v_fmac_f32_e32 v67, v74, v110
	v_fmac_f32_e32 v111, v78, v66
	v_fmac_f32_e32 v68, v80, v67
	v_fmac_f32_e32 v112, v80, v111
	v_fmac_f32_e32 v68, v74, v111
	v_fmac_f32_e32 v112, v78, v67
	v_fmac_f32_e32 v69, v80, v68
	v_fmac_f32_e32 v113, v80, v112
	v_fmac_f32_e32 v69, v74, v112
	v_fmac_f32_e32 v113, v78, v68
	s_waitcnt lgkmcnt(4)
	v_fmac_f32_e32 v70, v80, v69
	v_fmac_f32_e32 v114, v80, v113
	v_fmac_f32_e32 v70, v74, v113
	v_fmac_f32_e32 v114, v78, v69
	v_fmac_f32_e32 v71, v80, v70
	v_fmac_f32_e32 v115, v80, v114
	v_fmac_f32_e32 v71, v74, v114
	v_fmac_f32_e32 v115, v78, v70
	v_fmac_f32_e32 v72, v80, v71
	v_fmac_f32_e32 v116, v80, v115
	v_fmac_f32_e32 v72, v74, v115
	v_fmac_f32_e32 v116, v78, v71
	v_fmac_f32_e32 v73, v80, v72
	v_fmac_f32_e32 v117, v80, v116
	v_fmac_f32_e32 v73, v74, v116
	v_fmac_f32_e32 v117, v78, v72
	s_waitcnt lgkmcnt(2)
	v_fmac_f32_e32 v102, v80, v73
	v_fmac_f32_e32 v132, v80, v117
	v_fmac_f32_e32 v102, v74, v117
	v_fmac_f32_e32 v132, v78, v73
	v_fmac_f32_e32 v103, v80, v102
	v_fmac_f32_e32 v133, v80, v132
	v_fmac_f32_e32 v103, v74, v132
	v_fmac_f32_e32 v133, v78, v102
	v_fmac_f32_e32 v104, v80, v103
	v_fmac_f32_e32 v134, v80, v133
	v_fmac_f32_e32 v104, v74, v133
	v_fmac_f32_e32 v134, v78, v103
	v_fmac_f32_e32 v105, v80, v104
	v_fmac_f32_e32 v135, v80, v134
	v_fmac_f32_e32 v105, v74, v134
	v_fmac_f32_e32 v135, v78, v104
	s_waitcnt lgkmcnt(0)
	v_fmac_f32_e32 v106, v80, v105
	v_fmac_f32_e32 v136, v80, v135
	v_fmac_f32_e32 v106, v74, v135
	v_fmac_f32_e32 v136, v78, v105
	v_fmac_f32_e32 v107, v80, v106
	v_fmac_f32_e32 v137, v80, v136
	v_fmac_f32_e32 v107, v74, v136
	v_fmac_f32_e32 v137, v78, v106
	v_fmac_f32_e32 v108, v80, v107
	v_fmac_f32_e32 v138, v80, v137
	v_fmac_f32_e32 v108, v74, v137
	v_fmac_f32_e32 v138, v78, v107
	v_fmac_f32_e32 v109, v80, v108
	v_fmac_f32_e32 v139, v80, v138
	v_fmac_f32_e32 v109, v74, v138
	v_fmac_f32_e32 v139, v78, v108
	v_mov_b32_e32 v99, v109
	v_mov_b32_e32 v98, v139
	v_mfma_f32_16x16x32_bf16 v[66:69], v[198:201], v[10:13], 0
	v_mfma_f32_16x16x32_bf16 v[70:73], v[198:201], v[6:9], 0
	v_mfma_f32_16x16x32_bf16 v[102:105], v[198:201], v[18:21], 0
	v_mfma_f32_16x16x32_bf16 v[106:109], v[198:201], v[14:17], 0
	v_mfma_f32_16x16x32_bf16 v[110:113], v[198:201], v[26:29], 0
	v_mfma_f32_16x16x32_bf16 v[114:117], v[198:201], v[22:25], 0
	v_mfma_f32_16x16x32_bf16 v[132:135], v[198:201], v[34:37], 0
	v_mfma_f32_16x16x32_bf16 v[136:139], v[198:201], v[30:33], 0
	s_nop 0
	ds_write_b128 v128, v[66:69]
	ds_write_b128 v128, v[70:73] offset:1280
	ds_write_b128 v128, v[102:105] offset:2560
	ds_write_b128 v128, v[106:109] offset:3840
	ds_write_b128 v128, v[110:113] offset:5120
	ds_write_b128 v128, v[114:117] offset:6400
	ds_write_b128 v128, v[132:135] offset:7680
	ds_write_b128 v128, v[136:139] offset:8960
	s_waitcnt lgkmcnt(0)
	ds_read_b128 v[66:69], v130
	ds_read_b128 v[110:113], v130 offset:5120
	ds_read_b128 v[70:73], v130 offset:16
	ds_read_b128 v[114:117], v130 offset:5136
	ds_read_b128 v[102:105], v130 offset:32
	ds_read_b128 v[132:135], v130 offset:5152
	ds_read_b128 v[106:109], v130 offset:48
	ds_read_b128 v[136:139], v130 offset:5168
	s_waitcnt lgkmcnt(6)
	v_fmac_f32_e32 v66, v80, v99
	v_fmac_f32_e32 v110, v80, v98
	v_fmac_f32_e32 v66, v74, v98
	v_fmac_f32_e32 v110, v78, v99
	v_fmac_f32_e32 v67, v80, v66
	v_fmac_f32_e32 v111, v80, v110
	v_fmac_f32_e32 v67, v74, v110
	v_fmac_f32_e32 v111, v78, v66
	v_fmac_f32_e32 v68, v80, v67
	v_fmac_f32_e32 v112, v80, v111
	v_fmac_f32_e32 v68, v74, v111
	v_fmac_f32_e32 v112, v78, v67
	v_fmac_f32_e32 v69, v80, v68
	v_fmac_f32_e32 v113, v80, v112
	v_fmac_f32_e32 v69, v74, v112
	v_fmac_f32_e32 v113, v78, v68
	s_waitcnt lgkmcnt(4)
	v_fmac_f32_e32 v70, v80, v69
	v_fmac_f32_e32 v114, v80, v113
	v_fmac_f32_e32 v70, v74, v113
	v_fmac_f32_e32 v114, v78, v69
	v_fmac_f32_e32 v71, v80, v70
	v_fmac_f32_e32 v115, v80, v114
	v_fmac_f32_e32 v71, v74, v114
	v_fmac_f32_e32 v115, v78, v70
	v_fmac_f32_e32 v72, v80, v71
	v_fmac_f32_e32 v116, v80, v115
	v_fmac_f32_e32 v72, v74, v115
	v_fmac_f32_e32 v116, v78, v71
	v_fmac_f32_e32 v73, v80, v72
	v_fmac_f32_e32 v117, v80, v116
	v_fmac_f32_e32 v73, v74, v116
	v_fmac_f32_e32 v117, v78, v72
	s_waitcnt lgkmcnt(2)
	v_fmac_f32_e32 v102, v80, v73
	v_fmac_f32_e32 v132, v80, v117
	v_fmac_f32_e32 v102, v74, v117
	v_fmac_f32_e32 v132, v78, v73
	v_fmac_f32_e32 v103, v80, v102
	v_fmac_f32_e32 v133, v80, v132
	v_fmac_f32_e32 v103, v74, v132
	v_fmac_f32_e32 v133, v78, v102
	v_fmac_f32_e32 v104, v80, v103
	v_fmac_f32_e32 v134, v80, v133
	v_fmac_f32_e32 v104, v74, v133
	v_fmac_f32_e32 v134, v78, v103
	v_fmac_f32_e32 v105, v80, v104
	v_fmac_f32_e32 v135, v80, v134
	v_fmac_f32_e32 v105, v74, v134
	v_fmac_f32_e32 v135, v78, v104
	s_waitcnt lgkmcnt(0)
	v_fmac_f32_e32 v106, v80, v105
	v_fmac_f32_e32 v136, v80, v135
	v_fmac_f32_e32 v106, v74, v135
	v_fmac_f32_e32 v136, v78, v105
	v_fmac_f32_e32 v107, v80, v106
	v_fmac_f32_e32 v137, v80, v136
	v_fmac_f32_e32 v107, v74, v136
	v_fmac_f32_e32 v137, v78, v106
	v_fmac_f32_e32 v108, v80, v107
	v_fmac_f32_e32 v138, v80, v137
	v_fmac_f32_e32 v108, v74, v137
	v_fmac_f32_e32 v138, v78, v107
	v_fmac_f32_e32 v109, v80, v108
	v_fmac_f32_e32 v139, v80, v138
	v_fmac_f32_e32 v109, v74, v138
	v_fmac_f32_e32 v139, v78, v108
	v_mov_b32_e32 v99, v109
	v_mov_b32_e32 v98, v139
	s_add_u32 s24, s24, 0x90000
	s_addc_u32 s25, s25, 0
	s_cmp_lg_u32 s24, 0x240000
	s_cbranch_scc0 .LBB0_346
	s_waitcnt vmcnt(0)
	v_mov_b64_e32 v[186:187], v[202:203]
	v_mov_b64_e32 v[188:189], v[204:205]
	v_mov_b64_e32 v[190:191], v[206:207]
	v_mov_b64_e32 v[192:193], v[208:209]
	v_mov_b64_e32 v[194:195], v[210:211]
	v_mov_b64_e32 v[196:197], v[212:213]
	v_mov_b64_e32 v[198:199], v[214:215]
	v_mov_b64_e32 v[200:201], v[216:217]
	s_branch .Ls5p_loop0

.LBB0_790:
	s_or_b64 exec, exec, s[0:1]
	s_mov_b32 s0, 0x420000
	v_cmp_gt_i32_e32 vcc, s0, v184
	s_waitcnt lgkmcnt(0)
	s_barrier
	v_readfirstlane_b32 s0, v0
	v_and_b32_e32 v1, 0xff, v0
	v_and_b32_e32 v3, 15, v0
	s_lshr_b32 s0, s0, 8
	s_lshl_b32 s1, s59, 1
	s_add_u32 s8, s1, s0
	s_lshl_b32 s9, s58, 1
	s_mul_i32 s10, s9, 10
	v_lshlrev_b32_e32 v1, 4, v1
	v_lshlrev_b32_e32 v3, 2, v3
	v_mov_b32_e32 v2, 0x358637bd
	global_load_dwordx4 v[4:7], v1, s[72:73]
.Lp7_batch:
	s_add_u32 s13, s8, s10
	s_cmp_lt_u32 s13, 16896
	s_cbranch_scc0 .Lp7_tail
	s_mov_b32 s11, s8
	s_lshl_b32 s12, s11, 12
	s_add_u32 s16, s74, s12
	s_addc_u32 s17, s75, 0
	s_lshl_b32 s12, s11, 6
	s_add_u32 s76, s6, s12
	s_addc_u32 s77, s7, 0
	global_load_dword v8, v3, s[76:77]
	global_load_dwordx4 v[20:23], v1, s[16:17]
	s_add_u32 s11, s11, s9
	s_lshl_b32 s12, s11, 12
	s_add_u32 s18, s74, s12
	s_addc_u32 s19, s75, 0
	s_lshl_b32 s12, s11, 6
	s_add_u32 s78, s6, s12
	s_addc_u32 s79, s7, 0
	global_load_dword v9, v3, s[78:79]
	global_load_dwordx4 v[24:27], v1, s[18:19]
	s_add_u32 s11, s11, s9
	s_lshl_b32 s12, s11, 12
	s_add_u32 s20, s74, s12
	s_addc_u32 s21, s75, 0
	s_lshl_b32 s12, s11, 6
	s_add_u32 s80, s6, s12
	s_addc_u32 s81, s7, 0
	global_load_dword v10, v3, s[80:81]
	global_load_dwordx4 v[28:31], v1, s[20:21]
	s_add_u32 s11, s11, s9
	s_lshl_b32 s12, s11, 12
	s_add_u32 s22, s74, s12
	s_addc_u32 s23, s75, 0
	s_lshl_b32 s12, s11, 6
	s_add_u32 s82, s6, s12
	s_addc_u32 s83, s7, 0
	global_load_dword v11, v3, s[82:83]
	global_load_dwordx4 v[32:35], v1, s[22:23]
	s_add_u32 s11, s11, s9
	s_lshl_b32 s12, s11, 12
	s_add_u32 s24, s74, s12
	s_addc_u32 s25, s75, 0
	s_lshl_b32 s12, s11, 6
	s_add_u32 s84, s6, s12
	s_addc_u32 s85, s7, 0
	global_load_dword v12, v3, s[84:85]
	global_load_dwordx4 v[36:39], v1, s[24:25]
	s_add_u32 s11, s11, s9
	s_lshl_b32 s12, s11, 12
	s_add_u32 s26, s74, s12
	s_addc_u32 s27, s75, 0
	s_lshl_b32 s12, s11, 6
	s_add_u32 s86, s6, s12
	s_addc_u32 s87, s7, 0
	global_load_dword v13, v3, s[86:87]
	global_load_dwordx4 v[40:43], v1, s[26:27]
	s_add_u32 s11, s11, s9
	s_lshl_b32 s12, s11, 12
	s_add_u32 s28, s74, s12
	s_addc_u32 s29, s75, 0
	s_lshl_b32 s12, s11, 6
	s_add_u32 s88, s6, s12
	s_addc_u32 s89, s7, 0
	global_load_dword v14, v3, s[88:89]
	global_load_dwordx4 v[44:47], v1, s[28:29]
	s_add_u32 s11, s11, s9
	s_lshl_b32 s12, s11, 12
	s_add_u32 s30, s74, s12
	s_addc_u32 s31, s75, 0
	s_lshl_b32 s12, s11, 6
	s_add_u32 s90, s6, s12
	s_addc_u32 s91, s7, 0
	global_load_dword v15, v3, s[90:91]
	global_load_dwordx4 v[48:51], v1, s[30:31]
	s_add_u32 s11, s11, s9
	s_lshl_b32 s12, s11, 12
	s_add_u32 s32, s74, s12
	s_addc_u32 s33, s75, 0
	s_lshl_b32 s12, s11, 6
	s_add_u32 s92, s6, s12
	s_addc_u32 s93, s7, 0
	global_load_dword v16, v3, s[92:93]
	global_load_dwordx4 v[52:55], v1, s[32:33]
	s_add_u32 s11, s11, s9
	s_lshl_b32 s12, s11, 12
	s_add_u32 s34, s74, s12
	s_addc_u32 s35, s75, 0
	s_lshl_b32 s12, s11, 6
	s_add_u32 s94, s6, s12
	s_addc_u32 s95, s7, 0
	global_load_dword v17, v3, s[94:95]
	global_load_dwordx4 v[56:59], v1, s[34:35]
	s_add_u32 s11, s11, s9
	s_lshl_b32 s12, s11, 12
	s_add_u32 s36, s74, s12
	s_addc_u32 s37, s75, 0
	s_lshl_b32 s12, s11, 6
	s_add_u32 s96, s6, s12
	s_addc_u32 s97, s7, 0
	global_load_dword v18, v3, s[96:97]
	global_load_dwordx4 v[60:63], v1, s[36:37]
	s_waitcnt vmcnt(20)
	v_add_f32_dpp v8, v8, v8 quad_perm:[1,0,3,2] row_mask:0xf bank_mask:0xf
	s_nop 1
	v_add_f32_dpp v8, v8, v8 quad_perm:[2,3,0,1] row_mask:0xf bank_mask:0xf
	s_nop 1
	v_add_f32_dpp v8, v8, v8 row_half_mirror row_mask:0xf bank_mask:0xf
	s_nop 1
	v_add_f32_dpp v8, v8, v8 row_mirror row_mask:0xf bank_mask:0xf
	v_fmamk_f32 v8, v8, 0x3a800000, v2
	v_rsq_f32_e32 v8, v8
	s_nop 0
	v_mul_f32_e32 v20, v20, v8
	v_mul_f32_e32 v21, v21, v8
	v_mul_f32_e32 v22, v22, v8
	v_mul_f32_e32 v23, v23, v8
	v_mul_f32_e32 v20, v4, v20
	v_mul_f32_e32 v21, v5, v21
	v_mul_f32_e32 v22, v6, v22
	v_mul_f32_e32 v23, v7, v23
	global_store_dwordx4 v1, v[20:23], s[16:17]
	s_waitcnt vmcnt(19)
	v_add_f32_dpp v9, v9, v9 quad_perm:[1,0,3,2] row_mask:0xf bank_mask:0xf
	s_nop 1
	v_add_f32_dpp v9, v9, v9 quad_perm:[2,3,0,1] row_mask:0xf bank_mask:0xf
	s_nop 1
	v_add_f32_dpp v9, v9, v9 row_half_mirror row_mask:0xf bank_mask:0xf
	s_nop 1
	v_add_f32_dpp v9, v9, v9 row_mirror row_mask:0xf bank_mask:0xf
	v_fmamk_f32 v9, v9, 0x3a800000, v2
	v_rsq_f32_e32 v9, v9
	s_nop 0
	v_mul_f32_e32 v24, v24, v9
	v_mul_f32_e32 v25, v25, v9
	v_mul_f32_e32 v26, v26, v9
	v_mul_f32_e32 v27, v27, v9
	v_mul_f32_e32 v24, v4, v24
	v_mul_f32_e32 v25, v5, v25
	v_mul_f32_e32 v26, v6, v26
	v_mul_f32_e32 v27, v7, v27
	global_store_dwordx4 v1, v[24:27], s[18:19]
	s_waitcnt vmcnt(18)
	v_add_f32_dpp v10, v10, v10 quad_perm:[1,0,3,2] row_mask:0xf bank_mask:0xf
	s_nop 1
	v_add_f32_dpp v10, v10, v10 quad_perm:[2,3,0,1] row_mask:0xf bank_mask:0xf
	s_nop 1
	v_add_f32_dpp v10, v10, v10 row_half_mirror row_mask:0xf bank_mask:0xf
	s_nop 1
	v_add_f32_dpp v10, v10, v10 row_mirror row_mask:0xf bank_mask:0xf
	v_fmamk_f32 v10, v10, 0x3a800000, v2
	v_rsq_f32_e32 v10, v10
	s_nop 0
	v_mul_f32_e32 v28, v28, v10
	v_mul_f32_e32 v29, v29, v10
	v_mul_f32_e32 v30, v30, v10
	v_mul_f32_e32 v31, v31, v10
	v_mul_f32_e32 v28, v4, v28
	v_mul_f32_e32 v29, v5, v29
	v_mul_f32_e32 v30, v6, v30
	v_mul_f32_e32 v31, v7, v31
	global_store_dwordx4 v1, v[28:31], s[20:21]
	s_waitcnt vmcnt(17)
	v_add_f32_dpp v11, v11, v11 quad_perm:[1,0,3,2] row_mask:0xf bank_mask:0xf
	s_nop 1
	v_add_f32_dpp v11, v11, v11 quad_perm:[2,3,0,1] row_mask:0xf bank_mask:0xf
	s_nop 1
	v_add_f32_dpp v11, v11, v11 row_half_mirror row_mask:0xf bank_mask:0xf
	s_nop 1
	v_add_f32_dpp v11, v11, v11 row_mirror row_mask:0xf bank_mask:0xf
	v_fmamk_f32 v11, v11, 0x3a800000, v2
	v_rsq_f32_e32 v11, v11
	s_nop 0
	v_mul_f32_e32 v32, v32, v11
	v_mul_f32_e32 v33, v33, v11
	v_mul_f32_e32 v34, v34, v11
	v_mul_f32_e32 v35, v35, v11
	v_mul_f32_e32 v32, v4, v32
	v_mul_f32_e32 v33, v5, v33
	v_mul_f32_e32 v34, v6, v34
	v_mul_f32_e32 v35, v7, v35
	global_store_dwordx4 v1, v[32:35], s[22:23]
	s_waitcnt vmcnt(16)
	v_add_f32_dpp v12, v12, v12 quad_perm:[1,0,3,2] row_mask:0xf bank_mask:0xf
	s_nop 1
	v_add_f32_dpp v12, v12, v12 quad_perm:[2,3,0,1] row_mask:0xf bank_mask:0xf
	s_nop 1
	v_add_f32_dpp v12, v12, v12 row_half_mirror row_mask:0xf bank_mask:0xf
	s_nop 1
	v_add_f32_dpp v12, v12, v12 row_mirror row_mask:0xf bank_mask:0xf
	v_fmamk_f32 v12, v12, 0x3a800000, v2
	v_rsq_f32_e32 v12, v12
	s_nop 0
	v_mul_f32_e32 v36, v36, v12
	v_mul_f32_e32 v37, v37, v12
	v_mul_f32_e32 v38, v38, v12
	v_mul_f32_e32 v39, v39, v12
	v_mul_f32_e32 v36, v4, v36
	v_mul_f32_e32 v37, v5, v37
	v_mul_f32_e32 v38, v6, v38
	v_mul_f32_e32 v39, v7, v39
	global_store_dwordx4 v1, v[36:39], s[24:25]
	s_waitcnt vmcnt(15)
	v_add_f32_dpp v13, v13, v13 quad_perm:[1,0,3,2] row_mask:0xf bank_mask:0xf
	s_nop 1
	v_add_f32_dpp v13, v13, v13 quad_perm:[2,3,0,1] row_mask:0xf bank_mask:0xf
	s_nop 1
	v_add_f32_dpp v13, v13, v13 row_half_mirror row_mask:0xf bank_mask:0xf
	s_nop 1
	v_add_f32_dpp v13, v13, v13 row_mirror row_mask:0xf bank_mask:0xf
	v_fmamk_f32 v13, v13, 0x3a800000, v2
	v_rsq_f32_e32 v13, v13
	s_nop 0
	v_mul_f32_e32 v40, v40, v13
	v_mul_f32_e32 v41, v41, v13
	v_mul_f32_e32 v42, v42, v13
	v_mul_f32_e32 v43, v43, v13
	v_mul_f32_e32 v40, v4, v40
	v_mul_f32_e32 v41, v5, v41
	v_mul_f32_e32 v42, v6, v42
	v_mul_f32_e32 v43, v7, v43
	global_store_dwordx4 v1, v[40:43], s[26:27]
	s_waitcnt vmcnt(14)
	v_add_f32_dpp v14, v14, v14 quad_perm:[1,0,3,2] row_mask:0xf bank_mask:0xf
	s_nop 1
	v_add_f32_dpp v14, v14, v14 quad_perm:[2,3,0,1] row_mask:0xf bank_mask:0xf
	s_nop 1
	v_add_f32_dpp v14, v14, v14 row_half_mirror row_mask:0xf bank_mask:0xf
	s_nop 1
	v_add_f32_dpp v14, v14, v14 row_mirror row_mask:0xf bank_mask:0xf
	v_fmamk_f32 v14, v14, 0x3a800000, v2
	v_rsq_f32_e32 v14, v14
	s_nop 0
	v_mul_f32_e32 v44, v44, v14
	v_mul_f32_e32 v45, v45, v14
	v_mul_f32_e32 v46, v46, v14
	v_mul_f32_e32 v47, v47, v14
	v_mul_f32_e32 v44, v4, v44
	v_mul_f32_e32 v45, v5, v45
	v_mul_f32_e32 v46, v6, v46
	v_mul_f32_e32 v47, v7, v47
	global_store_dwordx4 v1, v[44:47], s[28:29]
	s_waitcnt vmcnt(13)
	v_add_f32_dpp v15, v15, v15 quad_perm:[1,0,3,2] row_mask:0xf bank_mask:0xf
	s_nop 1
	v_add_f32_dpp v15, v15, v15 quad_perm:[2,3,0,1] row_mask:0xf bank_mask:0xf
	s_nop 1
	v_add_f32_dpp v15, v15, v15 row_half_mirror row_mask:0xf bank_mask:0xf
	s_nop 1
	v_add_f32_dpp v15, v15, v15 row_mirror row_mask:0xf bank_mask:0xf
	v_fmamk_f32 v15, v15, 0x3a800000, v2
	v_rsq_f32_e32 v15, v15
	s_nop 0
	v_mul_f32_e32 v48, v48, v15
	v_mul_f32_e32 v49, v49, v15
	v_mul_f32_e32 v50, v50, v15
	v_mul_f32_e32 v51, v51, v15
	v_mul_f32_e32 v48, v4, v48
	v_mul_f32_e32 v49, v5, v49
	v_mul_f32_e32 v50, v6, v50
	v_mul_f32_e32 v51, v7, v51
	global_store_dwordx4 v1, v[48:51], s[30:31]
	s_waitcnt vmcnt(12)
	v_add_f32_dpp v16, v16, v16 quad_perm:[1,0,3,2] row_mask:0xf bank_mask:0xf
	s_nop 1
	v_add_f32_dpp v16, v16, v16 quad_perm:[2,3,0,1] row_mask:0xf bank_mask:0xf
	s_nop 1
	v_add_f32_dpp v16, v16, v16 row_half_mirror row_mask:0xf bank_mask:0xf
	s_nop 1
	v_add_f32_dpp v16, v16, v16 row_mirror row_mask:0xf bank_mask:0xf
	v_fmamk_f32 v16, v16, 0x3a800000, v2
	v_rsq_f32_e32 v16, v16
	s_nop 0
	v_mul_f32_e32 v52, v52, v16
	v_mul_f32_e32 v53, v53, v16
	v_mul_f32_e32 v54, v54, v16
	v_mul_f32_e32 v55, v55, v16
	v_mul_f32_e32 v52, v4, v52
	v_mul_f32_e32 v53, v5, v53
	v_mul_f32_e32 v54, v6, v54
	v_mul_f32_e32 v55, v7, v55
	global_store_dwordx4 v1, v[52:55], s[32:33]
	s_waitcnt vmcnt(11)
	v_add_f32_dpp v17, v17, v17 quad_perm:[1,0,3,2] row_mask:0xf bank_mask:0xf
	s_nop 1
	v_add_f32_dpp v17, v17, v17 quad_perm:[2,3,0,1] row_mask:0xf bank_mask:0xf
	s_nop 1
	v_add_f32_dpp v17, v17, v17 row_half_mirror row_mask:0xf bank_mask:0xf
	s_nop 1
	v_add_f32_dpp v17, v17, v17 row_mirror row_mask:0xf bank_mask:0xf
	v_fmamk_f32 v17, v17, 0x3a800000, v2
	v_rsq_f32_e32 v17, v17
	s_nop 0
	v_mul_f32_e32 v56, v56, v17
	v_mul_f32_e32 v57, v57, v17
	v_mul_f32_e32 v58, v58, v17
	v_mul_f32_e32 v59, v59, v17
	v_mul_f32_e32 v56, v4, v56
	v_mul_f32_e32 v57, v5, v57
	v_mul_f32_e32 v58, v6, v58
	v_mul_f32_e32 v59, v7, v59
	global_store_dwordx4 v1, v[56:59], s[34:35]
	s_waitcnt vmcnt(10)
	v_add_f32_dpp v18, v18, v18 quad_perm:[1,0,3,2] row_mask:0xf bank_mask:0xf
	s_nop 1
	v_add_f32_dpp v18, v18, v18 quad_perm:[2,3,0,1] row_mask:0xf bank_mask:0xf
	s_nop 1
	v_add_f32_dpp v18, v18, v18 row_half_mirror row_mask:0xf bank_mask:0xf
	s_nop 1
	v_add_f32_dpp v18, v18, v18 row_mirror row_mask:0xf bank_mask:0xf
	v_fmamk_f32 v18, v18, 0x3a800000, v2
	v_rsq_f32_e32 v18, v18
	s_nop 0
	v_mul_f32_e32 v60, v60, v18
	v_mul_f32_e32 v61, v61, v18
	v_mul_f32_e32 v62, v62, v18
	v_mul_f32_e32 v63, v63, v18
	v_mul_f32_e32 v60, v4, v60
	v_mul_f32_e32 v61, v5, v61
	v_mul_f32_e32 v62, v6, v62
	v_mul_f32_e32 v63, v7, v63
	global_store_dwordx4 v1, v[60:63], s[36:37]
	s_add_u32 s8, s13, s9
	s_branch .Lp7_batch
.Lp7_tail:
	s_cmp_lt_u32 s8, 16896
	s_cbranch_scc0 .LBB0_793
	s_mov_b32 s11, s8
	s_lshl_b32 s12, s11, 12
	s_add_u32 s16, s74, s12
	s_addc_u32 s17, s75, 0
	s_lshl_b32 s12, s11, 6
	s_add_u32 s76, s6, s12
	s_addc_u32 s77, s7, 0
	global_load_dword v8, v3, s[76:77]
	global_load_dwordx4 v[20:23], v1, s[16:17]
	s_waitcnt vmcnt(0)
	v_add_f32_dpp v8, v8, v8 quad_perm:[1,0,3,2] row_mask:0xf bank_mask:0xf
	s_nop 1
	v_add_f32_dpp v8, v8, v8 quad_perm:[2,3,0,1] row_mask:0xf bank_mask:0xf
	s_nop 1
	v_add_f32_dpp v8, v8, v8 row_half_mirror row_mask:0xf bank_mask:0xf
	s_nop 1
	v_add_f32_dpp v8, v8, v8 row_mirror row_mask:0xf bank_mask:0xf
	v_fmamk_f32 v8, v8, 0x3a800000, v2
	v_rsq_f32_e32 v8, v8
	s_nop 0
	v_mul_f32_e32 v20, v20, v8
	v_mul_f32_e32 v21, v21, v8
	v_mul_f32_e32 v22, v22, v8
	v_mul_f32_e32 v23, v23, v8
	v_mul_f32_e32 v20, v4, v20
	v_mul_f32_e32 v21, v5, v21
	v_mul_f32_e32 v22, v6, v22
	v_mul_f32_e32 v23, v7, v23
	global_store_dwordx4 v1, v[20:23], s[16:17]
	s_add_u32 s8, s8, s9
	s_branch .Lp7_tail
